# DeltaNet prep forward substitution: waves skip the all-zero rows above their columns (lower-triangular inverse) and column groups are paired so the two waves of a SIMD get complementary row counts; 4-
# speedup vs baseline: 1.0028x; 1.0028x over previous
.LBB0_523:
	v_and_b32_e32 v2, 7, v80
	v_lshrrev_b32_e32 v0, 3, v81
	v_readfirstlane_b32 s44, v10
	s_nop 0
	s_lshr_b32 s44, s44, 3
	s_sub_i32 s45, 11, s44
	s_cmp_lt_u32 s44, 4
	s_cselect_b32 s44, s44, s45
	s_lshl_b32 s45, s44, 3
	v_add_u32_e32 v0, s45, v0
	v_lshlrev_b32_e32 v128, 5, v2
	v_add_u32_e32 v128, 0xd400, v128
	v_mov_b32_e32 v129, 0xd400
	v_cmp_eq_u32_e64 s[6:7], 0, v2
	v_cmp_eq_u32_e64 s[8:9], 1, v2
	v_cmp_eq_u32_e64 s[10:11], 2, v2
	v_cmp_eq_u32_e64 s[12:13], 3, v2
	v_cmp_eq_u32_e64 s[14:15], 4, v2
	v_cmp_eq_u32_e64 s[16:17], 5, v2
	v_cmp_eq_u32_e64 s[18:19], 6, v2
	v_cmp_eq_u32_e64 s[20:21], 7, v2
	v_mov_b32_e32 v101, 0
	v_mov_b32_e32 v102, 0
	v_mov_b32_e32 v103, 0
	v_mov_b32_e32 v104, 0
	v_mov_b32_e32 v105, 0
	v_mov_b32_e32 v106, 0
	v_mov_b32_e32 v107, 0
	v_or_b32_e32 v152, v2, v0
	v_cmp_eq_u32_e32 vcc, 0, v152
	s_nop 1
	v_cndmask_b32_e64 v100, 0, 1.0, vcc
	s_cmp_eq_u32 s44, 1
	s_cbranch_scc1 .Lsv_p1
	s_cmp_eq_u32 s44, 2
	s_cbranch_scc1 .Lsv_p2
	s_cmp_eq_u32 s44, 3
	s_cbranch_scc1 .Lsv_p3
	s_cmp_eq_u32 s44, 4
	s_cbranch_scc1 .Lsv_p4
	s_cmp_eq_u32 s44, 5
	s_cbranch_scc1 .Lsv_p5
	s_cmp_eq_u32 s44, 6
	s_cbranch_scc1 .Lsv_p6
	s_cmp_eq_u32 s44, 7
	s_cbranch_scc1 .Lsv_p7
	s_branch .Lsv_c0
.Lsv_p1:
	ds_read_b128 v[206:209], v128 offset:2048
	ds_read_b128 v[214:217], v128 offset:2304
	ds_read_b128 v[222:225], v128 offset:2560
	ds_read_b128 v[230:233], v128 offset:2816
	ds_read_b32 v130, v129 offset:2308
	ds_read_b32 v131, v129 offset:2564
	ds_read_b32 v132, v129 offset:2596
	ds_read_b32 v133, v129 offset:2820
	ds_read_b32 v134, v129 offset:2852
	ds_read_b32 v135, v129 offset:2884
	v_mov_b32_e32 v108, 0
	v_mov_b32_e32 v109, 0
	v_mov_b32_e32 v110, 0
	v_mov_b32_e32 v111, 0
	v_cmp_eq_u32_e32 vcc, 8, v0
	s_nop 1
	v_cndmask_b32_e64 v116, 0, 1.0, vcc
	v_cmp_eq_u32_e32 vcc, 9, v0
	s_nop 1
	v_cndmask_b32_e64 v117, 0, 1.0, vcc
	v_cmp_eq_u32_e32 vcc, 10, v0
	s_nop 1
	v_cndmask_b32_e64 v118, 0, 1.0, vcc
	v_cmp_eq_u32_e32 vcc, 11, v0
	s_nop 1
	v_cndmask_b32_e64 v119, 0, 1.0, vcc
	s_branch .Lsv_b2
.Lsv_p2:
	ds_read_b128 v[206:209], v128 offset:4096
	ds_read_b128 v[214:217], v128 offset:4352
	ds_read_b128 v[222:225], v128 offset:4608
	ds_read_b128 v[230:233], v128 offset:4864
	ds_read_b32 v130, v129 offset:4360
	ds_read_b32 v131, v129 offset:4616
	ds_read_b32 v132, v129 offset:4648
	ds_read_b32 v133, v129 offset:4872
	ds_read_b32 v134, v129 offset:4904
	ds_read_b32 v135, v129 offset:4936
	v_mov_b32_e32 v108, 0
	v_mov_b32_e32 v109, 0
	v_mov_b32_e32 v110, 0
	v_mov_b32_e32 v111, 0
	v_cmp_eq_u32_e32 vcc, 16, v0
	s_nop 1
	v_cndmask_b32_e64 v116, 0, 1.0, vcc
	v_cmp_eq_u32_e32 vcc, 17, v0
	s_nop 1
	v_cndmask_b32_e64 v117, 0, 1.0, vcc
	v_cmp_eq_u32_e32 vcc, 18, v0
	s_nop 1
	v_cndmask_b32_e64 v118, 0, 1.0, vcc
	v_cmp_eq_u32_e32 vcc, 19, v0
	s_nop 1
	v_cndmask_b32_e64 v119, 0, 1.0, vcc
	s_branch .Lsv_b4
.Lsv_p3:
	ds_read_b128 v[206:209], v128 offset:6144
	ds_read_b128 v[214:217], v128 offset:6400
	ds_read_b128 v[222:225], v128 offset:6656
	ds_read_b128 v[230:233], v128 offset:6912
	ds_read_b32 v130, v129 offset:6412
	ds_read_b32 v131, v129 offset:6668
	ds_read_b32 v132, v129 offset:6700
	ds_read_b32 v133, v129 offset:6924
	ds_read_b32 v134, v129 offset:6956
	ds_read_b32 v135, v129 offset:6988
	v_mov_b32_e32 v108, 0
	v_mov_b32_e32 v109, 0
	v_mov_b32_e32 v110, 0
	v_mov_b32_e32 v111, 0
	v_cmp_eq_u32_e32 vcc, 24, v0
	s_nop 1
	v_cndmask_b32_e64 v116, 0, 1.0, vcc
	v_cmp_eq_u32_e32 vcc, 25, v0
	s_nop 1
	v_cndmask_b32_e64 v117, 0, 1.0, vcc
	v_cmp_eq_u32_e32 vcc, 26, v0
	s_nop 1
	v_cndmask_b32_e64 v118, 0, 1.0, vcc
	v_cmp_eq_u32_e32 vcc, 27, v0
	s_nop 1
	v_cndmask_b32_e64 v119, 0, 1.0, vcc
	s_branch .Lsv_b6
.Lsv_p4:
	ds_read_b128 v[206:209], v128 offset:8192
	ds_read_b128 v[214:217], v128 offset:8448
	ds_read_b128 v[222:225], v128 offset:8704
	ds_read_b128 v[230:233], v128 offset:8960
	ds_read_b32 v130, v129 offset:8464
	ds_read_b32 v131, v129 offset:8720
	ds_read_b32 v132, v129 offset:8752
	ds_read_b32 v133, v129 offset:8976
	ds_read_b32 v134, v129 offset:9008
	ds_read_b32 v135, v129 offset:9040
	v_mov_b32_e32 v108, 0
	v_mov_b32_e32 v109, 0
	v_mov_b32_e32 v110, 0
	v_mov_b32_e32 v111, 0
	v_cmp_eq_u32_e32 vcc, 32, v0
	s_nop 1
	v_cndmask_b32_e64 v116, 0, 1.0, vcc
	v_cmp_eq_u32_e32 vcc, 33, v0
	s_nop 1
	v_cndmask_b32_e64 v117, 0, 1.0, vcc
	v_cmp_eq_u32_e32 vcc, 34, v0
	s_nop 1
	v_cndmask_b32_e64 v118, 0, 1.0, vcc
	v_cmp_eq_u32_e32 vcc, 35, v0
	s_nop 1
	v_cndmask_b32_e64 v119, 0, 1.0, vcc
	s_branch .Lsv_b8
.Lsv_p5:
	ds_read_b128 v[206:209], v128 offset:10240
	ds_read_b128 v[210:213], v128 offset:10256
	ds_read_b128 v[214:217], v128 offset:10496
	ds_read_b128 v[218:221], v128 offset:10512
	ds_read_b128 v[222:225], v128 offset:10752
	ds_read_b128 v[226:229], v128 offset:10768
	ds_read_b128 v[230:233], v128 offset:11008
	ds_read_b128 v[234:237], v128 offset:11024
	ds_read_b32 v130, v129 offset:10516
	ds_read_b32 v131, v129 offset:10772
	ds_read_b32 v132, v129 offset:10804
	ds_read_b32 v133, v129 offset:11028
	ds_read_b32 v134, v129 offset:11060
	ds_read_b32 v135, v129 offset:11092
	v_mov_b32_e32 v108, 0
	v_mov_b32_e32 v109, 0
	v_mov_b32_e32 v110, 0
	v_mov_b32_e32 v111, 0
	v_cmp_eq_u32_e32 vcc, 40, v0
	s_nop 1
	v_cndmask_b32_e64 v116, 0, 1.0, vcc
	v_cmp_eq_u32_e32 vcc, 41, v0
	s_nop 1
	v_cndmask_b32_e64 v117, 0, 1.0, vcc
	v_cmp_eq_u32_e32 vcc, 42, v0
	s_nop 1
	v_cndmask_b32_e64 v118, 0, 1.0, vcc
	v_cmp_eq_u32_e32 vcc, 43, v0
	s_nop 1
	v_cndmask_b32_e64 v119, 0, 1.0, vcc
	s_branch .Lsv_b10
.Lsv_p6:
	ds_read_b128 v[206:209], v128 offset:12288
	ds_read_b128 v[210:213], v128 offset:12304
	ds_read_b128 v[214:217], v128 offset:12544
	ds_read_b128 v[218:221], v128 offset:12560
	ds_read_b128 v[222:225], v128 offset:12800
	ds_read_b128 v[226:229], v128 offset:12816
	ds_read_b128 v[230:233], v128 offset:13056
	ds_read_b128 v[234:237], v128 offset:13072
	ds_read_b32 v130, v129 offset:12568
	ds_read_b32 v131, v129 offset:12824
	ds_read_b32 v132, v129 offset:12856
	ds_read_b32 v133, v129 offset:13080
	ds_read_b32 v134, v129 offset:13112
	ds_read_b32 v135, v129 offset:13144
	v_mov_b32_e32 v108, 0
	v_mov_b32_e32 v109, 0
	v_mov_b32_e32 v110, 0
	v_mov_b32_e32 v111, 0
	v_cmp_eq_u32_e32 vcc, 48, v0
	s_nop 1
	v_cndmask_b32_e64 v116, 0, 1.0, vcc
	v_cmp_eq_u32_e32 vcc, 49, v0
	s_nop 1
	v_cndmask_b32_e64 v117, 0, 1.0, vcc
	v_cmp_eq_u32_e32 vcc, 50, v0
	s_nop 1
	v_cndmask_b32_e64 v118, 0, 1.0, vcc
	v_cmp_eq_u32_e32 vcc, 51, v0
	s_nop 1
	v_cndmask_b32_e64 v119, 0, 1.0, vcc
	s_branch .Lsv_b12
.Lsv_p7:
	ds_read_b128 v[206:209], v128 offset:14336
	ds_read_b128 v[210:213], v128 offset:14352
	ds_read_b128 v[214:217], v128 offset:14592
	ds_read_b128 v[218:221], v128 offset:14608
	ds_read_b128 v[222:225], v128 offset:14848
	ds_read_b128 v[226:229], v128 offset:14864
	ds_read_b128 v[230:233], v128 offset:15104
	ds_read_b128 v[234:237], v128 offset:15120
	ds_read_b32 v130, v129 offset:14620
	ds_read_b32 v131, v129 offset:14876
	ds_read_b32 v132, v129 offset:14908
	ds_read_b32 v133, v129 offset:15132
	ds_read_b32 v134, v129 offset:15164
	ds_read_b32 v135, v129 offset:15196
	v_mov_b32_e32 v108, 0
	v_mov_b32_e32 v109, 0
	v_mov_b32_e32 v110, 0
	v_mov_b32_e32 v111, 0
	v_cmp_eq_u32_e32 vcc, 56, v0
	s_nop 1
	v_cndmask_b32_e64 v116, 0, 1.0, vcc
	v_cmp_eq_u32_e32 vcc, 57, v0
	s_nop 1
	v_cndmask_b32_e64 v117, 0, 1.0, vcc
	v_cmp_eq_u32_e32 vcc, 58, v0
	s_nop 1
	v_cndmask_b32_e64 v118, 0, 1.0, vcc
	v_cmp_eq_u32_e32 vcc, 59, v0
	s_nop 1
	v_cndmask_b32_e64 v119, 0, 1.0, vcc
	s_branch .Lsv_b14
.Lsv_c0:
	ds_read_b128 v[206:209], v128 offset:256
	ds_read_b128 v[214:217], v128 offset:512
	ds_read_b128 v[222:225], v128 offset:768
	ds_read_b32 v130, v129 offset:544
	ds_read_b32 v131, v129 offset:800
	ds_read_b32 v132, v129 offset:832
	v_cmp_eq_u32_e32 vcc, 1, v0
	s_nop 1
	v_cndmask_b32_e64 v116, 0, 1.0, vcc
	v_cmp_eq_u32_e32 vcc, 2, v0
	s_nop 1
	v_cndmask_b32_e64 v117, 0, 1.0, vcc
	v_cmp_eq_u32_e32 vcc, 3, v0
	s_nop 1
	v_cndmask_b32_e64 v118, 0, 1.0, vcc
	s_waitcnt lgkmcnt(5)
	v_mul_f32_e32 v108, v206, v100
	s_waitcnt lgkmcnt(4)
	v_mul_f32_e32 v109, v214, v100
	s_waitcnt lgkmcnt(3)
	v_mul_f32_e32 v110, v222, v100
	s_waitcnt lgkmcnt(0)
	ds_read_b128 v[176:179], v128 offset:1024
	ds_read_b128 v[184:187], v128 offset:1280
	ds_read_b128 v[192:195], v128 offset:1536
	ds_read_b128 v[200:203], v128 offset:1792
	ds_read_b32 v146, v129 offset:1408
	ds_read_b32 v147, v129 offset:1664
	ds_read_b32 v148, v129 offset:1696
	ds_read_b32 v149, v129 offset:1920
	ds_read_b32 v150, v129 offset:1952
	ds_read_b32 v151, v129 offset:1984
	v_add_f32_dpp v108, v108, v108 quad_perm:[1,0,3,2] row_mask:0xf bank_mask:0xf bound_ctrl:1
	v_add_f32_dpp v109, v109, v109 quad_perm:[1,0,3,2] row_mask:0xf bank_mask:0xf bound_ctrl:1
	v_cmp_eq_u32_e32 vcc, 4, v0
	v_add_f32_dpp v110, v110, v110 quad_perm:[1,0,3,2] row_mask:0xf bank_mask:0xf bound_ctrl:1
	s_nop 0
	v_cndmask_b32_e64 v120, 0, 1.0, vcc
	v_cmp_eq_u32_e32 vcc, 5, v0
	v_add_f32_dpp v108, v108, v108 quad_perm:[2,3,0,1] row_mask:0xf bank_mask:0xf bound_ctrl:1
	v_add_f32_dpp v109, v109, v109 quad_perm:[2,3,0,1] row_mask:0xf bank_mask:0xf bound_ctrl:1
	v_cndmask_b32_e64 v121, 0, 1.0, vcc
	v_cmp_eq_u32_e32 vcc, 6, v0
	v_add_f32_dpp v110, v110, v110 quad_perm:[2,3,0,1] row_mask:0xf bank_mask:0xf bound_ctrl:1
	s_nop 0
	v_cndmask_b32_e64 v122, 0, 1.0, vcc
	v_cmp_eq_u32_e32 vcc, 7, v0
	v_add_f32_dpp v108, v108, v108 row_half_mirror row_mask:0xf bank_mask:0xf bound_ctrl:1
	v_add_f32_dpp v109, v109, v109 row_half_mirror row_mask:0xf bank_mask:0xf bound_ctrl:1
	v_cndmask_b32_e64 v123, 0, 1.0, vcc
	v_add_f32_dpp v110, v110, v110 row_half_mirror row_mask:0xf bank_mask:0xf bound_ctrl:1
	v_sub_f32_e32 v124, v116, v108
	v_sub_f32_e32 v125, v117, v109
	v_sub_f32_e32 v126, v118, v110
	v_fma_f32 v125, -v130, v124, v125
	v_fma_f32 v126, -v131, v124, v126
	v_fma_f32 v126, -v132, v125, v126
	v_cndmask_b32_e64 v100, v100, v124, s[8:9]
	v_cndmask_b32_e64 v100, v100, v125, s[10:11]
	v_cndmask_b32_e64 v100, v100, v126, s[12:13]
	s_waitcnt lgkmcnt(9)
	v_mul_f32_e32 v112, v176, v100
	s_waitcnt lgkmcnt(8)
	v_mul_f32_e32 v113, v184, v100
	s_waitcnt lgkmcnt(7)
	v_mul_f32_e32 v114, v192, v100
	s_waitcnt lgkmcnt(6)
	v_mul_f32_e32 v115, v200, v100
	s_waitcnt lgkmcnt(0)
	ds_read_b128 v[206:209], v128 offset:2048
	ds_read_b128 v[214:217], v128 offset:2304
	ds_read_b128 v[222:225], v128 offset:2560
	ds_read_b128 v[230:233], v128 offset:2816
	ds_read_b32 v130, v129 offset:2308
	ds_read_b32 v131, v129 offset:2564
	ds_read_b32 v132, v129 offset:2596
	ds_read_b32 v133, v129 offset:2820
	ds_read_b32 v134, v129 offset:2852
	ds_read_b32 v135, v129 offset:2884
	v_add_f32_dpp v112, v112, v112 quad_perm:[1,0,3,2] row_mask:0xf bank_mask:0xf bound_ctrl:1
	v_add_f32_dpp v113, v113, v113 quad_perm:[1,0,3,2] row_mask:0xf bank_mask:0xf bound_ctrl:1
	v_cmp_eq_u32_e32 vcc, 8, v0
	v_add_f32_dpp v114, v114, v114 quad_perm:[1,0,3,2] row_mask:0xf bank_mask:0xf bound_ctrl:1
	v_add_f32_dpp v115, v115, v115 quad_perm:[1,0,3,2] row_mask:0xf bank_mask:0xf bound_ctrl:1
	v_cndmask_b32_e64 v116, 0, 1.0, vcc
	v_cmp_eq_u32_e32 vcc, 9, v0
	v_add_f32_dpp v112, v112, v112 quad_perm:[2,3,0,1] row_mask:0xf bank_mask:0xf bound_ctrl:1
	v_add_f32_dpp v113, v113, v113 quad_perm:[2,3,0,1] row_mask:0xf bank_mask:0xf bound_ctrl:1
	v_cndmask_b32_e64 v117, 0, 1.0, vcc
	v_cmp_eq_u32_e32 vcc, 10, v0
	v_add_f32_dpp v114, v114, v114 quad_perm:[2,3,0,1] row_mask:0xf bank_mask:0xf bound_ctrl:1
	v_add_f32_dpp v115, v115, v115 quad_perm:[2,3,0,1] row_mask:0xf bank_mask:0xf bound_ctrl:1
	v_cndmask_b32_e64 v118, 0, 1.0, vcc
	v_cmp_eq_u32_e32 vcc, 11, v0
	v_add_f32_dpp v112, v112, v112 row_half_mirror row_mask:0xf bank_mask:0xf bound_ctrl:1
	v_add_f32_dpp v113, v113, v113 row_half_mirror row_mask:0xf bank_mask:0xf bound_ctrl:1
	v_cndmask_b32_e64 v119, 0, 1.0, vcc
	v_add_f32_dpp v114, v114, v114 row_half_mirror row_mask:0xf bank_mask:0xf bound_ctrl:1
	v_add_f32_dpp v115, v115, v115 row_half_mirror row_mask:0xf bank_mask:0xf bound_ctrl:1
	v_sub_f32_e32 v124, v120, v112
	v_sub_f32_e32 v125, v121, v113
	v_sub_f32_e32 v126, v122, v114
	v_sub_f32_e32 v127, v123, v115
	v_fma_f32 v125, -v146, v124, v125
	v_fma_f32 v126, -v147, v124, v126
	v_fma_f32 v127, -v149, v124, v127
	v_fma_f32 v126, -v148, v125, v126
	v_fma_f32 v127, -v150, v125, v127
	v_fma_f32 v127, -v151, v126, v127
	v_cndmask_b32_e64 v100, v100, v124, s[14:15]
	v_cndmask_b32_e64 v100, v100, v125, s[16:17]
	v_cndmask_b32_e64 v100, v100, v126, s[18:19]
	v_cndmask_b32_e64 v100, v100, v127, s[20:21]
.Lsv_b2:
	s_waitcnt lgkmcnt(9)
	v_mul_f32_e32 v108, v206, v100
	s_waitcnt lgkmcnt(8)
	v_mul_f32_e32 v109, v214, v100
	s_waitcnt lgkmcnt(7)
	v_mul_f32_e32 v110, v222, v100
	s_waitcnt lgkmcnt(6)
	v_mul_f32_e32 v111, v230, v100
	s_waitcnt lgkmcnt(0)
	ds_read_b128 v[176:179], v128 offset:3072
	ds_read_b128 v[184:187], v128 offset:3328
	ds_read_b128 v[192:195], v128 offset:3584
	ds_read_b128 v[200:203], v128 offset:3840
	ds_read_b32 v146, v129 offset:3460
	ds_read_b32 v147, v129 offset:3716
	ds_read_b32 v148, v129 offset:3748
	ds_read_b32 v149, v129 offset:3972
	ds_read_b32 v150, v129 offset:4004
	ds_read_b32 v151, v129 offset:4036
	v_add_f32_dpp v108, v108, v108 quad_perm:[1,0,3,2] row_mask:0xf bank_mask:0xf bound_ctrl:1
	v_add_f32_dpp v109, v109, v109 quad_perm:[1,0,3,2] row_mask:0xf bank_mask:0xf bound_ctrl:1
	v_cmp_eq_u32_e32 vcc, 12, v0
	v_add_f32_dpp v110, v110, v110 quad_perm:[1,0,3,2] row_mask:0xf bank_mask:0xf bound_ctrl:1
	v_add_f32_dpp v111, v111, v111 quad_perm:[1,0,3,2] row_mask:0xf bank_mask:0xf bound_ctrl:1
	v_cndmask_b32_e64 v120, 0, 1.0, vcc
	v_cmp_eq_u32_e32 vcc, 13, v0
	v_add_f32_dpp v108, v108, v108 quad_perm:[2,3,0,1] row_mask:0xf bank_mask:0xf bound_ctrl:1
	v_add_f32_dpp v109, v109, v109 quad_perm:[2,3,0,1] row_mask:0xf bank_mask:0xf bound_ctrl:1
	v_cndmask_b32_e64 v121, 0, 1.0, vcc
	v_cmp_eq_u32_e32 vcc, 14, v0
	v_add_f32_dpp v110, v110, v110 quad_perm:[2,3,0,1] row_mask:0xf bank_mask:0xf bound_ctrl:1
	v_add_f32_dpp v111, v111, v111 quad_perm:[2,3,0,1] row_mask:0xf bank_mask:0xf bound_ctrl:1
	v_cndmask_b32_e64 v122, 0, 1.0, vcc
	v_cmp_eq_u32_e32 vcc, 15, v0
	v_add_f32_dpp v108, v108, v108 row_half_mirror row_mask:0xf bank_mask:0xf bound_ctrl:1
	v_add_f32_dpp v109, v109, v109 row_half_mirror row_mask:0xf bank_mask:0xf bound_ctrl:1
	v_cndmask_b32_e64 v123, 0, 1.0, vcc
	v_add_f32_dpp v110, v110, v110 row_half_mirror row_mask:0xf bank_mask:0xf bound_ctrl:1
	v_add_f32_dpp v111, v111, v111 row_half_mirror row_mask:0xf bank_mask:0xf bound_ctrl:1
	v_sub_f32_e32 v124, v116, v108
	v_sub_f32_e32 v125, v117, v109
	v_sub_f32_e32 v126, v118, v110
	v_sub_f32_e32 v127, v119, v111
	v_fma_f32 v125, -v130, v124, v125
	v_fma_f32 v126, -v131, v124, v126
	v_fma_f32 v127, -v133, v124, v127
	s_waitcnt lgkmcnt(9)
	v_mul_f32_e32 v112, v176, v100
	s_waitcnt lgkmcnt(8)
	v_mul_f32_e32 v113, v184, v100
	v_fma_f32 v126, -v132, v125, v126
	v_fma_f32 v127, -v134, v125, v127
	s_waitcnt lgkmcnt(7)
	v_mul_f32_e32 v114, v192, v100
	s_waitcnt lgkmcnt(6)
	v_mul_f32_e32 v115, v200, v100
	v_fma_f32 v127, -v135, v126, v127
	v_cndmask_b32_e64 v101, v101, v124, s[6:7]
	v_cndmask_b32_e64 v101, v101, v125, s[8:9]
	v_cndmask_b32_e64 v101, v101, v126, s[10:11]
	v_cndmask_b32_e64 v101, v101, v127, s[12:13]
	v_fmac_f32_e32 v112, v177, v101
	v_fmac_f32_e32 v113, v185, v101
	v_fmac_f32_e32 v114, v193, v101
	v_fmac_f32_e32 v115, v201, v101
	s_waitcnt lgkmcnt(0)
	ds_read_b128 v[206:209], v128 offset:4096
	ds_read_b128 v[214:217], v128 offset:4352
	ds_read_b128 v[222:225], v128 offset:4608
	ds_read_b128 v[230:233], v128 offset:4864
	ds_read_b32 v130, v129 offset:4360
	ds_read_b32 v131, v129 offset:4616
	ds_read_b32 v132, v129 offset:4648
	ds_read_b32 v133, v129 offset:4872
	ds_read_b32 v134, v129 offset:4904
	ds_read_b32 v135, v129 offset:4936
	v_add_f32_dpp v112, v112, v112 quad_perm:[1,0,3,2] row_mask:0xf bank_mask:0xf bound_ctrl:1
	v_add_f32_dpp v113, v113, v113 quad_perm:[1,0,3,2] row_mask:0xf bank_mask:0xf bound_ctrl:1
	v_cmp_eq_u32_e32 vcc, 16, v0
	v_add_f32_dpp v114, v114, v114 quad_perm:[1,0,3,2] row_mask:0xf bank_mask:0xf bound_ctrl:1
	v_add_f32_dpp v115, v115, v115 quad_perm:[1,0,3,2] row_mask:0xf bank_mask:0xf bound_ctrl:1
	v_cndmask_b32_e64 v116, 0, 1.0, vcc
	v_cmp_eq_u32_e32 vcc, 17, v0
	v_add_f32_dpp v112, v112, v112 quad_perm:[2,3,0,1] row_mask:0xf bank_mask:0xf bound_ctrl:1
	v_add_f32_dpp v113, v113, v113 quad_perm:[2,3,0,1] row_mask:0xf bank_mask:0xf bound_ctrl:1
	v_cndmask_b32_e64 v117, 0, 1.0, vcc
	v_cmp_eq_u32_e32 vcc, 18, v0
	v_add_f32_dpp v114, v114, v114 quad_perm:[2,3,0,1] row_mask:0xf bank_mask:0xf bound_ctrl:1
	v_add_f32_dpp v115, v115, v115 quad_perm:[2,3,0,1] row_mask:0xf bank_mask:0xf bound_ctrl:1
	v_cndmask_b32_e64 v118, 0, 1.0, vcc
	v_cmp_eq_u32_e32 vcc, 19, v0
	v_add_f32_dpp v112, v112, v112 row_half_mirror row_mask:0xf bank_mask:0xf bound_ctrl:1
	v_add_f32_dpp v113, v113, v113 row_half_mirror row_mask:0xf bank_mask:0xf bound_ctrl:1
	v_cndmask_b32_e64 v119, 0, 1.0, vcc
	v_add_f32_dpp v114, v114, v114 row_half_mirror row_mask:0xf bank_mask:0xf bound_ctrl:1
	v_add_f32_dpp v115, v115, v115 row_half_mirror row_mask:0xf bank_mask:0xf bound_ctrl:1
	v_sub_f32_e32 v124, v120, v112
	v_sub_f32_e32 v125, v121, v113
	v_sub_f32_e32 v126, v122, v114
	v_sub_f32_e32 v127, v123, v115
	v_fma_f32 v125, -v146, v124, v125
	v_fma_f32 v126, -v147, v124, v126
	v_fma_f32 v127, -v149, v124, v127
	s_waitcnt lgkmcnt(9)
	v_mul_f32_e32 v108, v206, v100
	s_waitcnt lgkmcnt(8)
	v_mul_f32_e32 v109, v214, v100
	v_fma_f32 v126, -v148, v125, v126
	v_fma_f32 v127, -v150, v125, v127
	s_waitcnt lgkmcnt(7)
	v_mul_f32_e32 v110, v222, v100
	s_waitcnt lgkmcnt(6)
	v_mul_f32_e32 v111, v230, v100
	v_fma_f32 v127, -v151, v126, v127
	v_cndmask_b32_e64 v101, v101, v124, s[14:15]
	v_cndmask_b32_e64 v101, v101, v125, s[16:17]
	v_cndmask_b32_e64 v101, v101, v126, s[18:19]
	v_cndmask_b32_e64 v101, v101, v127, s[20:21]
.Lsv_b4:
	v_fmac_f32_e32 v108, v207, v101
	v_fmac_f32_e32 v109, v215, v101
	v_fmac_f32_e32 v110, v223, v101
	v_fmac_f32_e32 v111, v231, v101
	s_waitcnt lgkmcnt(0)
	ds_read_b128 v[176:179], v128 offset:5120
	ds_read_b128 v[184:187], v128 offset:5376
	ds_read_b128 v[192:195], v128 offset:5632
	ds_read_b128 v[200:203], v128 offset:5888
	ds_read_b32 v146, v129 offset:5512
	ds_read_b32 v147, v129 offset:5768
	ds_read_b32 v148, v129 offset:5800
	ds_read_b32 v149, v129 offset:6024
	ds_read_b32 v150, v129 offset:6056
	ds_read_b32 v151, v129 offset:6088
	v_add_f32_dpp v108, v108, v108 quad_perm:[1,0,3,2] row_mask:0xf bank_mask:0xf bound_ctrl:1
	v_add_f32_dpp v109, v109, v109 quad_perm:[1,0,3,2] row_mask:0xf bank_mask:0xf bound_ctrl:1
	v_cmp_eq_u32_e32 vcc, 20, v0
	v_add_f32_dpp v110, v110, v110 quad_perm:[1,0,3,2] row_mask:0xf bank_mask:0xf bound_ctrl:1
	v_add_f32_dpp v111, v111, v111 quad_perm:[1,0,3,2] row_mask:0xf bank_mask:0xf bound_ctrl:1
	v_cndmask_b32_e64 v120, 0, 1.0, vcc
	v_cmp_eq_u32_e32 vcc, 21, v0
	v_add_f32_dpp v108, v108, v108 quad_perm:[2,3,0,1] row_mask:0xf bank_mask:0xf bound_ctrl:1
	v_add_f32_dpp v109, v109, v109 quad_perm:[2,3,0,1] row_mask:0xf bank_mask:0xf bound_ctrl:1
	v_cndmask_b32_e64 v121, 0, 1.0, vcc
	v_cmp_eq_u32_e32 vcc, 22, v0
	v_add_f32_dpp v110, v110, v110 quad_perm:[2,3,0,1] row_mask:0xf bank_mask:0xf bound_ctrl:1
	v_add_f32_dpp v111, v111, v111 quad_perm:[2,3,0,1] row_mask:0xf bank_mask:0xf bound_ctrl:1
	v_cndmask_b32_e64 v122, 0, 1.0, vcc
	v_cmp_eq_u32_e32 vcc, 23, v0
	v_add_f32_dpp v108, v108, v108 row_half_mirror row_mask:0xf bank_mask:0xf bound_ctrl:1
	v_add_f32_dpp v109, v109, v109 row_half_mirror row_mask:0xf bank_mask:0xf bound_ctrl:1
	v_cndmask_b32_e64 v123, 0, 1.0, vcc
	v_add_f32_dpp v110, v110, v110 row_half_mirror row_mask:0xf bank_mask:0xf bound_ctrl:1
	v_add_f32_dpp v111, v111, v111 row_half_mirror row_mask:0xf bank_mask:0xf bound_ctrl:1
	v_sub_f32_e32 v124, v116, v108
	v_sub_f32_e32 v125, v117, v109
	v_sub_f32_e32 v126, v118, v110
	v_sub_f32_e32 v127, v119, v111
	v_fma_f32 v125, -v130, v124, v125
	v_fma_f32 v126, -v131, v124, v126
	v_fma_f32 v127, -v133, v124, v127
	s_waitcnt lgkmcnt(9)
	v_mul_f32_e32 v112, v176, v100
	s_waitcnt lgkmcnt(8)
	v_mul_f32_e32 v113, v184, v100
	v_fma_f32 v126, -v132, v125, v126
	v_fma_f32 v127, -v134, v125, v127
	s_waitcnt lgkmcnt(7)
	v_mul_f32_e32 v114, v192, v100
	s_waitcnt lgkmcnt(6)
	v_mul_f32_e32 v115, v200, v100
	v_fma_f32 v127, -v135, v126, v127
	v_fmac_f32_e32 v112, v177, v101
	v_fmac_f32_e32 v113, v185, v101
	v_cndmask_b32_e64 v102, v102, v124, s[6:7]
	v_fmac_f32_e32 v114, v193, v101
	v_cndmask_b32_e64 v102, v102, v125, s[8:9]
	v_fmac_f32_e32 v115, v201, v101
	v_cndmask_b32_e64 v102, v102, v126, s[10:11]
	v_cndmask_b32_e64 v102, v102, v127, s[12:13]
	v_fmac_f32_e32 v112, v178, v102
	v_fmac_f32_e32 v113, v186, v102
	v_fmac_f32_e32 v114, v194, v102
	v_fmac_f32_e32 v115, v202, v102
	s_waitcnt lgkmcnt(0)
	ds_read_b128 v[206:209], v128 offset:6144
	ds_read_b128 v[214:217], v128 offset:6400
	ds_read_b128 v[222:225], v128 offset:6656
	ds_read_b128 v[230:233], v128 offset:6912
	ds_read_b32 v130, v129 offset:6412
	ds_read_b32 v131, v129 offset:6668
	ds_read_b32 v132, v129 offset:6700
	ds_read_b32 v133, v129 offset:6924
	ds_read_b32 v134, v129 offset:6956
	ds_read_b32 v135, v129 offset:6988
	v_add_f32_dpp v112, v112, v112 quad_perm:[1,0,3,2] row_mask:0xf bank_mask:0xf bound_ctrl:1
	v_add_f32_dpp v113, v113, v113 quad_perm:[1,0,3,2] row_mask:0xf bank_mask:0xf bound_ctrl:1
	v_cmp_eq_u32_e32 vcc, 24, v0
	v_add_f32_dpp v114, v114, v114 quad_perm:[1,0,3,2] row_mask:0xf bank_mask:0xf bound_ctrl:1
	v_add_f32_dpp v115, v115, v115 quad_perm:[1,0,3,2] row_mask:0xf bank_mask:0xf bound_ctrl:1
	v_cndmask_b32_e64 v116, 0, 1.0, vcc
	v_cmp_eq_u32_e32 vcc, 25, v0
	v_add_f32_dpp v112, v112, v112 quad_perm:[2,3,0,1] row_mask:0xf bank_mask:0xf bound_ctrl:1
	v_add_f32_dpp v113, v113, v113 quad_perm:[2,3,0,1] row_mask:0xf bank_mask:0xf bound_ctrl:1
	v_cndmask_b32_e64 v117, 0, 1.0, vcc
	v_cmp_eq_u32_e32 vcc, 26, v0
	v_add_f32_dpp v114, v114, v114 quad_perm:[2,3,0,1] row_mask:0xf bank_mask:0xf bound_ctrl:1
	v_add_f32_dpp v115, v115, v115 quad_perm:[2,3,0,1] row_mask:0xf bank_mask:0xf bound_ctrl:1
	v_cndmask_b32_e64 v118, 0, 1.0, vcc
	v_cmp_eq_u32_e32 vcc, 27, v0
	v_add_f32_dpp v112, v112, v112 row_half_mirror row_mask:0xf bank_mask:0xf bound_ctrl:1
	v_add_f32_dpp v113, v113, v113 row_half_mirror row_mask:0xf bank_mask:0xf bound_ctrl:1
	v_cndmask_b32_e64 v119, 0, 1.0, vcc
	v_add_f32_dpp v114, v114, v114 row_half_mirror row_mask:0xf bank_mask:0xf bound_ctrl:1
	v_add_f32_dpp v115, v115, v115 row_half_mirror row_mask:0xf bank_mask:0xf bound_ctrl:1
	v_sub_f32_e32 v124, v120, v112
	v_sub_f32_e32 v125, v121, v113
	v_sub_f32_e32 v126, v122, v114
	v_sub_f32_e32 v127, v123, v115
	v_fma_f32 v125, -v146, v124, v125
	v_fma_f32 v126, -v147, v124, v126
	v_fma_f32 v127, -v149, v124, v127
	s_waitcnt lgkmcnt(9)
	v_mul_f32_e32 v108, v206, v100
	s_waitcnt lgkmcnt(8)
	v_mul_f32_e32 v109, v214, v100
	v_fma_f32 v126, -v148, v125, v126
	v_fma_f32 v127, -v150, v125, v127
	s_waitcnt lgkmcnt(7)
	v_mul_f32_e32 v110, v222, v100
	s_waitcnt lgkmcnt(6)
	v_mul_f32_e32 v111, v230, v100
	v_fma_f32 v127, -v151, v126, v127
	v_fmac_f32_e32 v108, v207, v101
	v_fmac_f32_e32 v109, v215, v101
	v_cndmask_b32_e64 v102, v102, v124, s[14:15]
	v_fmac_f32_e32 v110, v223, v101
	v_cndmask_b32_e64 v102, v102, v125, s[16:17]
	v_fmac_f32_e32 v111, v231, v101
	v_cndmask_b32_e64 v102, v102, v126, s[18:19]
	v_cndmask_b32_e64 v102, v102, v127, s[20:21]
.Lsv_b6:
	v_fmac_f32_e32 v108, v208, v102
	v_fmac_f32_e32 v109, v216, v102
	v_fmac_f32_e32 v110, v224, v102
	v_fmac_f32_e32 v111, v232, v102
	s_waitcnt lgkmcnt(0)
	ds_read_b128 v[176:179], v128 offset:7168
	ds_read_b128 v[184:187], v128 offset:7424
	ds_read_b128 v[192:195], v128 offset:7680
	ds_read_b128 v[200:203], v128 offset:7936
	ds_read_b32 v146, v129 offset:7564
	ds_read_b32 v147, v129 offset:7820
	ds_read_b32 v148, v129 offset:7852
	ds_read_b32 v149, v129 offset:8076
	ds_read_b32 v150, v129 offset:8108
	ds_read_b32 v151, v129 offset:8140
	v_add_f32_dpp v108, v108, v108 quad_perm:[1,0,3,2] row_mask:0xf bank_mask:0xf bound_ctrl:1
	v_add_f32_dpp v109, v109, v109 quad_perm:[1,0,3,2] row_mask:0xf bank_mask:0xf bound_ctrl:1
	v_cmp_eq_u32_e32 vcc, 28, v0
	v_add_f32_dpp v110, v110, v110 quad_perm:[1,0,3,2] row_mask:0xf bank_mask:0xf bound_ctrl:1
	v_add_f32_dpp v111, v111, v111 quad_perm:[1,0,3,2] row_mask:0xf bank_mask:0xf bound_ctrl:1
	v_cndmask_b32_e64 v120, 0, 1.0, vcc
	v_cmp_eq_u32_e32 vcc, 29, v0
	v_add_f32_dpp v108, v108, v108 quad_perm:[2,3,0,1] row_mask:0xf bank_mask:0xf bound_ctrl:1
	v_add_f32_dpp v109, v109, v109 quad_perm:[2,3,0,1] row_mask:0xf bank_mask:0xf bound_ctrl:1
	v_cndmask_b32_e64 v121, 0, 1.0, vcc
	v_cmp_eq_u32_e32 vcc, 30, v0
	v_add_f32_dpp v110, v110, v110 quad_perm:[2,3,0,1] row_mask:0xf bank_mask:0xf bound_ctrl:1
	v_add_f32_dpp v111, v111, v111 quad_perm:[2,3,0,1] row_mask:0xf bank_mask:0xf bound_ctrl:1
	v_cndmask_b32_e64 v122, 0, 1.0, vcc
	v_cmp_eq_u32_e32 vcc, 31, v0
	v_add_f32_dpp v108, v108, v108 row_half_mirror row_mask:0xf bank_mask:0xf bound_ctrl:1
	v_add_f32_dpp v109, v109, v109 row_half_mirror row_mask:0xf bank_mask:0xf bound_ctrl:1
	v_cndmask_b32_e64 v123, 0, 1.0, vcc
	v_add_f32_dpp v110, v110, v110 row_half_mirror row_mask:0xf bank_mask:0xf bound_ctrl:1
	v_add_f32_dpp v111, v111, v111 row_half_mirror row_mask:0xf bank_mask:0xf bound_ctrl:1
	v_sub_f32_e32 v124, v116, v108
	v_sub_f32_e32 v125, v117, v109
	v_sub_f32_e32 v126, v118, v110
	v_sub_f32_e32 v127, v119, v111
	v_fma_f32 v125, -v130, v124, v125
	v_fma_f32 v126, -v131, v124, v126
	v_fma_f32 v127, -v133, v124, v127
	s_waitcnt lgkmcnt(9)
	v_mul_f32_e32 v112, v176, v100
	s_waitcnt lgkmcnt(8)
	v_mul_f32_e32 v113, v184, v100
	v_fma_f32 v126, -v132, v125, v126
	v_fma_f32 v127, -v134, v125, v127
	s_waitcnt lgkmcnt(7)
	v_mul_f32_e32 v114, v192, v100
	s_waitcnt lgkmcnt(6)
	v_mul_f32_e32 v115, v200, v100
	v_fma_f32 v127, -v135, v126, v127
	v_fmac_f32_e32 v112, v177, v101
	v_fmac_f32_e32 v113, v185, v101
	v_cndmask_b32_e64 v103, v103, v124, s[6:7]
	v_fmac_f32_e32 v114, v193, v101
	v_cndmask_b32_e64 v103, v103, v125, s[8:9]
	v_fmac_f32_e32 v115, v201, v101
	v_cndmask_b32_e64 v103, v103, v126, s[10:11]
	v_fmac_f32_e32 v112, v178, v102
	v_cndmask_b32_e64 v103, v103, v127, s[12:13]
	v_fmac_f32_e32 v113, v186, v102
	v_fmac_f32_e32 v114, v194, v102
	v_fmac_f32_e32 v115, v202, v102
	v_fmac_f32_e32 v112, v179, v103
	v_fmac_f32_e32 v113, v187, v103
	v_fmac_f32_e32 v114, v195, v103
	v_fmac_f32_e32 v115, v203, v103
	s_waitcnt lgkmcnt(0)
	ds_read_b128 v[206:209], v128 offset:8192
	ds_read_b128 v[214:217], v128 offset:8448
	ds_read_b128 v[222:225], v128 offset:8704
	ds_read_b128 v[230:233], v128 offset:8960
	ds_read_b32 v130, v129 offset:8464
	ds_read_b32 v131, v129 offset:8720
	ds_read_b32 v132, v129 offset:8752
	ds_read_b32 v133, v129 offset:8976
	ds_read_b32 v134, v129 offset:9008
	ds_read_b32 v135, v129 offset:9040
	v_add_f32_dpp v112, v112, v112 quad_perm:[1,0,3,2] row_mask:0xf bank_mask:0xf bound_ctrl:1
	v_add_f32_dpp v113, v113, v113 quad_perm:[1,0,3,2] row_mask:0xf bank_mask:0xf bound_ctrl:1
	v_cmp_eq_u32_e32 vcc, 32, v0
	v_add_f32_dpp v114, v114, v114 quad_perm:[1,0,3,2] row_mask:0xf bank_mask:0xf bound_ctrl:1
	v_add_f32_dpp v115, v115, v115 quad_perm:[1,0,3,2] row_mask:0xf bank_mask:0xf bound_ctrl:1
	v_cndmask_b32_e64 v116, 0, 1.0, vcc
	v_cmp_eq_u32_e32 vcc, 33, v0
	v_add_f32_dpp v112, v112, v112 quad_perm:[2,3,0,1] row_mask:0xf bank_mask:0xf bound_ctrl:1
	v_add_f32_dpp v113, v113, v113 quad_perm:[2,3,0,1] row_mask:0xf bank_mask:0xf bound_ctrl:1
	v_cndmask_b32_e64 v117, 0, 1.0, vcc
	v_cmp_eq_u32_e32 vcc, 34, v0
	v_add_f32_dpp v114, v114, v114 quad_perm:[2,3,0,1] row_mask:0xf bank_mask:0xf bound_ctrl:1
	v_add_f32_dpp v115, v115, v115 quad_perm:[2,3,0,1] row_mask:0xf bank_mask:0xf bound_ctrl:1
	v_cndmask_b32_e64 v118, 0, 1.0, vcc
	v_cmp_eq_u32_e32 vcc, 35, v0
	v_add_f32_dpp v112, v112, v112 row_half_mirror row_mask:0xf bank_mask:0xf bound_ctrl:1
	v_add_f32_dpp v113, v113, v113 row_half_mirror row_mask:0xf bank_mask:0xf bound_ctrl:1
	v_cndmask_b32_e64 v119, 0, 1.0, vcc
	v_add_f32_dpp v114, v114, v114 row_half_mirror row_mask:0xf bank_mask:0xf bound_ctrl:1
	v_add_f32_dpp v115, v115, v115 row_half_mirror row_mask:0xf bank_mask:0xf bound_ctrl:1
	v_sub_f32_e32 v124, v120, v112
	v_sub_f32_e32 v125, v121, v113
	v_sub_f32_e32 v126, v122, v114
	v_sub_f32_e32 v127, v123, v115
	v_fma_f32 v125, -v146, v124, v125
	v_fma_f32 v126, -v147, v124, v126
	v_fma_f32 v127, -v149, v124, v127
	s_waitcnt lgkmcnt(9)
	v_mul_f32_e32 v108, v206, v100
	s_waitcnt lgkmcnt(8)
	v_mul_f32_e32 v109, v214, v100
	v_fma_f32 v126, -v148, v125, v126
	v_fma_f32 v127, -v150, v125, v127
	s_waitcnt lgkmcnt(7)
	v_mul_f32_e32 v110, v222, v100
	s_waitcnt lgkmcnt(6)
	v_mul_f32_e32 v111, v230, v100
	v_fma_f32 v127, -v151, v126, v127
	v_fmac_f32_e32 v108, v207, v101
	v_fmac_f32_e32 v109, v215, v101
	v_cndmask_b32_e64 v103, v103, v124, s[14:15]
	v_fmac_f32_e32 v110, v223, v101
	v_cndmask_b32_e64 v103, v103, v125, s[16:17]
	v_fmac_f32_e32 v111, v231, v101
	v_cndmask_b32_e64 v103, v103, v126, s[18:19]
	v_fmac_f32_e32 v108, v208, v102
	v_cndmask_b32_e64 v103, v103, v127, s[20:21]
	v_fmac_f32_e32 v109, v216, v102
	v_fmac_f32_e32 v110, v224, v102
	v_fmac_f32_e32 v111, v232, v102
.Lsv_b8:
	v_fmac_f32_e32 v108, v209, v103
	v_fmac_f32_e32 v109, v217, v103
	v_fmac_f32_e32 v110, v225, v103
	v_fmac_f32_e32 v111, v233, v103
	s_waitcnt lgkmcnt(0)
	ds_read_b128 v[176:179], v128 offset:9216
	ds_read_b128 v[180:183], v128 offset:9232
	ds_read_b128 v[184:187], v128 offset:9472
	ds_read_b128 v[188:191], v128 offset:9488
	ds_read_b128 v[192:195], v128 offset:9728
	ds_read_b128 v[196:199], v128 offset:9744
	ds_read_b128 v[200:203], v128 offset:9984
	ds_read_b128 v[238:241], v128 offset:10000
	ds_read_b32 v146, v129 offset:9616
	ds_read_b32 v147, v129 offset:9872
	ds_read_b32 v148, v129 offset:9904
	ds_read_b32 v149, v129 offset:10128
	ds_read_b32 v150, v129 offset:10160
	ds_read_b32 v151, v129 offset:10192
	v_add_f32_dpp v108, v108, v108 quad_perm:[1,0,3,2] row_mask:0xf bank_mask:0xf bound_ctrl:1
	v_add_f32_dpp v109, v109, v109 quad_perm:[1,0,3,2] row_mask:0xf bank_mask:0xf bound_ctrl:1
	v_cmp_eq_u32_e32 vcc, 36, v0
	v_add_f32_dpp v110, v110, v110 quad_perm:[1,0,3,2] row_mask:0xf bank_mask:0xf bound_ctrl:1
	v_add_f32_dpp v111, v111, v111 quad_perm:[1,0,3,2] row_mask:0xf bank_mask:0xf bound_ctrl:1
	v_cndmask_b32_e64 v120, 0, 1.0, vcc
	v_cmp_eq_u32_e32 vcc, 37, v0
	v_add_f32_dpp v108, v108, v108 quad_perm:[2,3,0,1] row_mask:0xf bank_mask:0xf bound_ctrl:1
	v_add_f32_dpp v109, v109, v109 quad_perm:[2,3,0,1] row_mask:0xf bank_mask:0xf bound_ctrl:1
	v_cndmask_b32_e64 v121, 0, 1.0, vcc
	v_cmp_eq_u32_e32 vcc, 38, v0
	v_add_f32_dpp v110, v110, v110 quad_perm:[2,3,0,1] row_mask:0xf bank_mask:0xf bound_ctrl:1
	v_add_f32_dpp v111, v111, v111 quad_perm:[2,3,0,1] row_mask:0xf bank_mask:0xf bound_ctrl:1
	v_cndmask_b32_e64 v122, 0, 1.0, vcc
	v_cmp_eq_u32_e32 vcc, 39, v0
	v_add_f32_dpp v108, v108, v108 row_half_mirror row_mask:0xf bank_mask:0xf bound_ctrl:1
	v_add_f32_dpp v109, v109, v109 row_half_mirror row_mask:0xf bank_mask:0xf bound_ctrl:1
	v_cndmask_b32_e64 v123, 0, 1.0, vcc
	v_add_f32_dpp v110, v110, v110 row_half_mirror row_mask:0xf bank_mask:0xf bound_ctrl:1
	v_add_f32_dpp v111, v111, v111 row_half_mirror row_mask:0xf bank_mask:0xf bound_ctrl:1
	v_sub_f32_e32 v124, v116, v108
	v_sub_f32_e32 v125, v117, v109
	v_sub_f32_e32 v126, v118, v110
	v_sub_f32_e32 v127, v119, v111
	v_fma_f32 v125, -v130, v124, v125
	v_fma_f32 v126, -v131, v124, v126
	v_fma_f32 v127, -v133, v124, v127
	s_waitcnt lgkmcnt(13)
	v_mul_f32_e32 v112, v176, v100
	s_waitcnt lgkmcnt(11)
	v_mul_f32_e32 v113, v184, v100
	v_fma_f32 v126, -v132, v125, v126
	v_fma_f32 v127, -v134, v125, v127
	s_waitcnt lgkmcnt(9)
	v_mul_f32_e32 v114, v192, v100
	s_waitcnt lgkmcnt(7)
	v_mul_f32_e32 v115, v200, v100
	v_fma_f32 v127, -v135, v126, v127
	v_fmac_f32_e32 v112, v177, v101
	v_fmac_f32_e32 v113, v185, v101
	v_cndmask_b32_e64 v104, v104, v124, s[6:7]
	v_fmac_f32_e32 v114, v193, v101
	v_cndmask_b32_e64 v104, v104, v125, s[8:9]
	v_fmac_f32_e32 v115, v201, v101
	v_cndmask_b32_e64 v104, v104, v126, s[10:11]
	v_fmac_f32_e32 v112, v178, v102
	v_cndmask_b32_e64 v104, v104, v127, s[12:13]
	v_fmac_f32_e32 v113, v186, v102
	v_fmac_f32_e32 v114, v194, v102
	v_fmac_f32_e32 v115, v202, v102
	v_fmac_f32_e32 v112, v179, v103
	v_fmac_f32_e32 v113, v187, v103
	v_fmac_f32_e32 v114, v195, v103
	v_fmac_f32_e32 v115, v203, v103
	v_fmac_f32_e32 v112, v180, v104
	v_fmac_f32_e32 v113, v188, v104
	v_fmac_f32_e32 v114, v196, v104
	s_waitcnt lgkmcnt(6)
	v_fmac_f32_e32 v115, v238, v104
	s_waitcnt lgkmcnt(0)
	ds_read_b128 v[206:209], v128 offset:10240
	ds_read_b128 v[210:213], v128 offset:10256
	ds_read_b128 v[214:217], v128 offset:10496
	ds_read_b128 v[218:221], v128 offset:10512
	ds_read_b128 v[222:225], v128 offset:10752
	ds_read_b128 v[226:229], v128 offset:10768
	ds_read_b128 v[230:233], v128 offset:11008
	ds_read_b128 v[234:237], v128 offset:11024
	ds_read_b32 v130, v129 offset:10516
	ds_read_b32 v131, v129 offset:10772
	ds_read_b32 v132, v129 offset:10804
	ds_read_b32 v133, v129 offset:11028
	ds_read_b32 v134, v129 offset:11060
	ds_read_b32 v135, v129 offset:11092
	v_add_f32_dpp v112, v112, v112 quad_perm:[1,0,3,2] row_mask:0xf bank_mask:0xf bound_ctrl:1
	v_add_f32_dpp v113, v113, v113 quad_perm:[1,0,3,2] row_mask:0xf bank_mask:0xf bound_ctrl:1
	v_cmp_eq_u32_e32 vcc, 40, v0
	v_add_f32_dpp v114, v114, v114 quad_perm:[1,0,3,2] row_mask:0xf bank_mask:0xf bound_ctrl:1
	v_add_f32_dpp v115, v115, v115 quad_perm:[1,0,3,2] row_mask:0xf bank_mask:0xf bound_ctrl:1
	v_cndmask_b32_e64 v116, 0, 1.0, vcc
	v_cmp_eq_u32_e32 vcc, 41, v0
	v_add_f32_dpp v112, v112, v112 quad_perm:[2,3,0,1] row_mask:0xf bank_mask:0xf bound_ctrl:1
	v_add_f32_dpp v113, v113, v113 quad_perm:[2,3,0,1] row_mask:0xf bank_mask:0xf bound_ctrl:1
	v_cndmask_b32_e64 v117, 0, 1.0, vcc
	v_cmp_eq_u32_e32 vcc, 42, v0
	v_add_f32_dpp v114, v114, v114 quad_perm:[2,3,0,1] row_mask:0xf bank_mask:0xf bound_ctrl:1
	v_add_f32_dpp v115, v115, v115 quad_perm:[2,3,0,1] row_mask:0xf bank_mask:0xf bound_ctrl:1
	v_cndmask_b32_e64 v118, 0, 1.0, vcc
	v_cmp_eq_u32_e32 vcc, 43, v0
	v_add_f32_dpp v112, v112, v112 row_half_mirror row_mask:0xf bank_mask:0xf bound_ctrl:1
	v_add_f32_dpp v113, v113, v113 row_half_mirror row_mask:0xf bank_mask:0xf bound_ctrl:1
	v_cndmask_b32_e64 v119, 0, 1.0, vcc
	v_add_f32_dpp v114, v114, v114 row_half_mirror row_mask:0xf bank_mask:0xf bound_ctrl:1
	v_add_f32_dpp v115, v115, v115 row_half_mirror row_mask:0xf bank_mask:0xf bound_ctrl:1
	v_sub_f32_e32 v124, v120, v112
	v_sub_f32_e32 v125, v121, v113
	v_sub_f32_e32 v126, v122, v114
	v_sub_f32_e32 v127, v123, v115
	v_fma_f32 v125, -v146, v124, v125
	v_fma_f32 v126, -v147, v124, v126
	v_fma_f32 v127, -v149, v124, v127
	s_waitcnt lgkmcnt(13)
	v_mul_f32_e32 v108, v206, v100
	s_waitcnt lgkmcnt(11)
	v_mul_f32_e32 v109, v214, v100
	v_fma_f32 v126, -v148, v125, v126
	v_fma_f32 v127, -v150, v125, v127
	s_waitcnt lgkmcnt(9)
	v_mul_f32_e32 v110, v222, v100
	s_waitcnt lgkmcnt(7)
	v_mul_f32_e32 v111, v230, v100
	v_fma_f32 v127, -v151, v126, v127
	v_fmac_f32_e32 v108, v207, v101
	v_fmac_f32_e32 v109, v215, v101
	v_cndmask_b32_e64 v104, v104, v124, s[14:15]
	v_fmac_f32_e32 v110, v223, v101
	v_cndmask_b32_e64 v104, v104, v125, s[16:17]
	v_fmac_f32_e32 v111, v231, v101
	v_cndmask_b32_e64 v104, v104, v126, s[18:19]
	v_fmac_f32_e32 v108, v208, v102
	v_cndmask_b32_e64 v104, v104, v127, s[20:21]
	v_fmac_f32_e32 v109, v216, v102
	v_fmac_f32_e32 v110, v224, v102
	v_fmac_f32_e32 v111, v232, v102
	v_fmac_f32_e32 v108, v209, v103
	v_fmac_f32_e32 v109, v217, v103
	v_fmac_f32_e32 v110, v225, v103
	v_fmac_f32_e32 v111, v233, v103
.Lsv_b10:
	v_fmac_f32_e32 v108, v210, v104
	v_fmac_f32_e32 v109, v218, v104
	v_fmac_f32_e32 v110, v226, v104
	s_waitcnt lgkmcnt(6)
	v_fmac_f32_e32 v111, v234, v104
	s_waitcnt lgkmcnt(0)
	ds_read_b128 v[176:179], v128 offset:11264
	ds_read_b128 v[180:183], v128 offset:11280
	ds_read_b128 v[184:187], v128 offset:11520
	ds_read_b128 v[188:191], v128 offset:11536
	ds_read_b128 v[192:195], v128 offset:11776
	ds_read_b128 v[196:199], v128 offset:11792
	ds_read_b128 v[200:203], v128 offset:12032
	ds_read_b128 v[238:241], v128 offset:12048
	ds_read_b32 v146, v129 offset:11668
	ds_read_b32 v147, v129 offset:11924
	ds_read_b32 v148, v129 offset:11956
	ds_read_b32 v149, v129 offset:12180
	ds_read_b32 v150, v129 offset:12212
	ds_read_b32 v151, v129 offset:12244
	v_add_f32_dpp v108, v108, v108 quad_perm:[1,0,3,2] row_mask:0xf bank_mask:0xf bound_ctrl:1
	v_add_f32_dpp v109, v109, v109 quad_perm:[1,0,3,2] row_mask:0xf bank_mask:0xf bound_ctrl:1
	v_cmp_eq_u32_e32 vcc, 44, v0
	v_add_f32_dpp v110, v110, v110 quad_perm:[1,0,3,2] row_mask:0xf bank_mask:0xf bound_ctrl:1
	v_add_f32_dpp v111, v111, v111 quad_perm:[1,0,3,2] row_mask:0xf bank_mask:0xf bound_ctrl:1
	v_cndmask_b32_e64 v120, 0, 1.0, vcc
	v_cmp_eq_u32_e32 vcc, 45, v0
	v_add_f32_dpp v108, v108, v108 quad_perm:[2,3,0,1] row_mask:0xf bank_mask:0xf bound_ctrl:1
	v_add_f32_dpp v109, v109, v109 quad_perm:[2,3,0,1] row_mask:0xf bank_mask:0xf bound_ctrl:1
	v_cndmask_b32_e64 v121, 0, 1.0, vcc
	v_cmp_eq_u32_e32 vcc, 46, v0
	v_add_f32_dpp v110, v110, v110 quad_perm:[2,3,0,1] row_mask:0xf bank_mask:0xf bound_ctrl:1
	v_add_f32_dpp v111, v111, v111 quad_perm:[2,3,0,1] row_mask:0xf bank_mask:0xf bound_ctrl:1
	v_cndmask_b32_e64 v122, 0, 1.0, vcc
	v_cmp_eq_u32_e32 vcc, 47, v0
	v_add_f32_dpp v108, v108, v108 row_half_mirror row_mask:0xf bank_mask:0xf bound_ctrl:1
	v_add_f32_dpp v109, v109, v109 row_half_mirror row_mask:0xf bank_mask:0xf bound_ctrl:1
	v_cndmask_b32_e64 v123, 0, 1.0, vcc
	v_add_f32_dpp v110, v110, v110 row_half_mirror row_mask:0xf bank_mask:0xf bound_ctrl:1
	v_add_f32_dpp v111, v111, v111 row_half_mirror row_mask:0xf bank_mask:0xf bound_ctrl:1
	v_sub_f32_e32 v124, v116, v108
	v_sub_f32_e32 v125, v117, v109
	v_sub_f32_e32 v126, v118, v110
	v_sub_f32_e32 v127, v119, v111
	v_fma_f32 v125, -v130, v124, v125
	v_fma_f32 v126, -v131, v124, v126
	v_fma_f32 v127, -v133, v124, v127
	s_waitcnt lgkmcnt(13)
	v_mul_f32_e32 v112, v176, v100
	s_waitcnt lgkmcnt(11)
	v_mul_f32_e32 v113, v184, v100
	v_fma_f32 v126, -v132, v125, v126
	v_fma_f32 v127, -v134, v125, v127
	s_waitcnt lgkmcnt(9)
	v_mul_f32_e32 v114, v192, v100
	s_waitcnt lgkmcnt(7)
	v_mul_f32_e32 v115, v200, v100
	v_fma_f32 v127, -v135, v126, v127
	v_fmac_f32_e32 v112, v177, v101
	v_fmac_f32_e32 v113, v185, v101
	v_cndmask_b32_e64 v105, v105, v124, s[6:7]
	v_fmac_f32_e32 v114, v193, v101
	v_cndmask_b32_e64 v105, v105, v125, s[8:9]
	v_fmac_f32_e32 v115, v201, v101
	v_cndmask_b32_e64 v105, v105, v126, s[10:11]
	v_fmac_f32_e32 v112, v178, v102
	v_cndmask_b32_e64 v105, v105, v127, s[12:13]
	v_fmac_f32_e32 v113, v186, v102
	v_fmac_f32_e32 v114, v194, v102
	v_fmac_f32_e32 v115, v202, v102
	v_fmac_f32_e32 v112, v179, v103
	v_fmac_f32_e32 v113, v187, v103
	v_fmac_f32_e32 v114, v195, v103
	v_fmac_f32_e32 v115, v203, v103
	v_fmac_f32_e32 v112, v180, v104
	v_fmac_f32_e32 v113, v188, v104
	v_fmac_f32_e32 v114, v196, v104
	s_waitcnt lgkmcnt(6)
	v_fmac_f32_e32 v115, v238, v104
	v_fmac_f32_e32 v112, v181, v105
	v_fmac_f32_e32 v113, v189, v105
	v_fmac_f32_e32 v114, v197, v105
	v_fmac_f32_e32 v115, v239, v105
	s_waitcnt lgkmcnt(0)
	ds_read_b128 v[206:209], v128 offset:12288
	ds_read_b128 v[210:213], v128 offset:12304
	ds_read_b128 v[214:217], v128 offset:12544
	ds_read_b128 v[218:221], v128 offset:12560
	ds_read_b128 v[222:225], v128 offset:12800
	ds_read_b128 v[226:229], v128 offset:12816
	ds_read_b128 v[230:233], v128 offset:13056
	ds_read_b128 v[234:237], v128 offset:13072
	ds_read_b32 v130, v129 offset:12568
	ds_read_b32 v131, v129 offset:12824
	ds_read_b32 v132, v129 offset:12856
	ds_read_b32 v133, v129 offset:13080
	ds_read_b32 v134, v129 offset:13112
	ds_read_b32 v135, v129 offset:13144
	v_add_f32_dpp v112, v112, v112 quad_perm:[1,0,3,2] row_mask:0xf bank_mask:0xf bound_ctrl:1
	v_add_f32_dpp v113, v113, v113 quad_perm:[1,0,3,2] row_mask:0xf bank_mask:0xf bound_ctrl:1
	v_cmp_eq_u32_e32 vcc, 48, v0
	v_add_f32_dpp v114, v114, v114 quad_perm:[1,0,3,2] row_mask:0xf bank_mask:0xf bound_ctrl:1
	v_add_f32_dpp v115, v115, v115 quad_perm:[1,0,3,2] row_mask:0xf bank_mask:0xf bound_ctrl:1
	v_cndmask_b32_e64 v116, 0, 1.0, vcc
	v_cmp_eq_u32_e32 vcc, 49, v0
	v_add_f32_dpp v112, v112, v112 quad_perm:[2,3,0,1] row_mask:0xf bank_mask:0xf bound_ctrl:1
	v_add_f32_dpp v113, v113, v113 quad_perm:[2,3,0,1] row_mask:0xf bank_mask:0xf bound_ctrl:1
	v_cndmask_b32_e64 v117, 0, 1.0, vcc
	v_cmp_eq_u32_e32 vcc, 50, v0
	v_add_f32_dpp v114, v114, v114 quad_perm:[2,3,0,1] row_mask:0xf bank_mask:0xf bound_ctrl:1
	v_add_f32_dpp v115, v115, v115 quad_perm:[2,3,0,1] row_mask:0xf bank_mask:0xf bound_ctrl:1
	v_cndmask_b32_e64 v118, 0, 1.0, vcc
	v_cmp_eq_u32_e32 vcc, 51, v0
	v_add_f32_dpp v112, v112, v112 row_half_mirror row_mask:0xf bank_mask:0xf bound_ctrl:1
	v_add_f32_dpp v113, v113, v113 row_half_mirror row_mask:0xf bank_mask:0xf bound_ctrl:1
	v_cndmask_b32_e64 v119, 0, 1.0, vcc
	v_add_f32_dpp v114, v114, v114 row_half_mirror row_mask:0xf bank_mask:0xf bound_ctrl:1
	v_add_f32_dpp v115, v115, v115 row_half_mirror row_mask:0xf bank_mask:0xf bound_ctrl:1
	v_sub_f32_e32 v124, v120, v112
	v_sub_f32_e32 v125, v121, v113
	v_sub_f32_e32 v126, v122, v114
	v_sub_f32_e32 v127, v123, v115
	v_fma_f32 v125, -v146, v124, v125
	v_fma_f32 v126, -v147, v124, v126
	v_fma_f32 v127, -v149, v124, v127
	s_waitcnt lgkmcnt(13)
	v_mul_f32_e32 v108, v206, v100
	s_waitcnt lgkmcnt(11)
	v_mul_f32_e32 v109, v214, v100
	v_fma_f32 v126, -v148, v125, v126
	v_fma_f32 v127, -v150, v125, v127
	s_waitcnt lgkmcnt(9)
	v_mul_f32_e32 v110, v222, v100
	s_waitcnt lgkmcnt(7)
	v_mul_f32_e32 v111, v230, v100
	v_fma_f32 v127, -v151, v126, v127
	v_fmac_f32_e32 v108, v207, v101
	v_fmac_f32_e32 v109, v215, v101
	v_cndmask_b32_e64 v105, v105, v124, s[14:15]
	v_fmac_f32_e32 v110, v223, v101
	v_cndmask_b32_e64 v105, v105, v125, s[16:17]
	v_fmac_f32_e32 v111, v231, v101
	v_cndmask_b32_e64 v105, v105, v126, s[18:19]
	v_fmac_f32_e32 v108, v208, v102
	v_cndmask_b32_e64 v105, v105, v127, s[20:21]
	v_fmac_f32_e32 v109, v216, v102
	v_fmac_f32_e32 v110, v224, v102
	v_fmac_f32_e32 v111, v232, v102
	v_fmac_f32_e32 v108, v209, v103
	v_fmac_f32_e32 v109, v217, v103
	v_fmac_f32_e32 v110, v225, v103
	v_fmac_f32_e32 v111, v233, v103
	v_fmac_f32_e32 v108, v210, v104
	v_fmac_f32_e32 v109, v218, v104
	v_fmac_f32_e32 v110, v226, v104
	s_waitcnt lgkmcnt(6)
	v_fmac_f32_e32 v111, v234, v104
.Lsv_b12:
	v_fmac_f32_e32 v108, v211, v105
	v_fmac_f32_e32 v109, v219, v105
	v_fmac_f32_e32 v110, v227, v105
	v_fmac_f32_e32 v111, v235, v105
	s_waitcnt lgkmcnt(0)
	ds_read_b128 v[176:179], v128 offset:13312
	ds_read_b128 v[180:183], v128 offset:13328
	ds_read_b128 v[184:187], v128 offset:13568
	ds_read_b128 v[188:191], v128 offset:13584
	ds_read_b128 v[192:195], v128 offset:13824
	ds_read_b128 v[196:199], v128 offset:13840
	ds_read_b128 v[200:203], v128 offset:14080
	ds_read_b128 v[238:241], v128 offset:14096
	ds_read_b32 v146, v129 offset:13720
	ds_read_b32 v147, v129 offset:13976
	ds_read_b32 v148, v129 offset:14008
	ds_read_b32 v149, v129 offset:14232
	ds_read_b32 v150, v129 offset:14264
	ds_read_b32 v151, v129 offset:14296
	v_add_f32_dpp v108, v108, v108 quad_perm:[1,0,3,2] row_mask:0xf bank_mask:0xf bound_ctrl:1
	v_add_f32_dpp v109, v109, v109 quad_perm:[1,0,3,2] row_mask:0xf bank_mask:0xf bound_ctrl:1
	v_cmp_eq_u32_e32 vcc, 52, v0
	v_add_f32_dpp v110, v110, v110 quad_perm:[1,0,3,2] row_mask:0xf bank_mask:0xf bound_ctrl:1
	v_add_f32_dpp v111, v111, v111 quad_perm:[1,0,3,2] row_mask:0xf bank_mask:0xf bound_ctrl:1
	v_cndmask_b32_e64 v120, 0, 1.0, vcc
	v_cmp_eq_u32_e32 vcc, 53, v0
	v_add_f32_dpp v108, v108, v108 quad_perm:[2,3,0,1] row_mask:0xf bank_mask:0xf bound_ctrl:1
	v_add_f32_dpp v109, v109, v109 quad_perm:[2,3,0,1] row_mask:0xf bank_mask:0xf bound_ctrl:1
	v_cndmask_b32_e64 v121, 0, 1.0, vcc
	v_cmp_eq_u32_e32 vcc, 54, v0
	v_add_f32_dpp v110, v110, v110 quad_perm:[2,3,0,1] row_mask:0xf bank_mask:0xf bound_ctrl:1
	v_add_f32_dpp v111, v111, v111 quad_perm:[2,3,0,1] row_mask:0xf bank_mask:0xf bound_ctrl:1
	v_cndmask_b32_e64 v122, 0, 1.0, vcc
	v_cmp_eq_u32_e32 vcc, 55, v0
	v_add_f32_dpp v108, v108, v108 row_half_mirror row_mask:0xf bank_mask:0xf bound_ctrl:1
	v_add_f32_dpp v109, v109, v109 row_half_mirror row_mask:0xf bank_mask:0xf bound_ctrl:1
	v_cndmask_b32_e64 v123, 0, 1.0, vcc
	v_add_f32_dpp v110, v110, v110 row_half_mirror row_mask:0xf bank_mask:0xf bound_ctrl:1
	v_add_f32_dpp v111, v111, v111 row_half_mirror row_mask:0xf bank_mask:0xf bound_ctrl:1
	v_sub_f32_e32 v124, v116, v108
	v_sub_f32_e32 v125, v117, v109
	v_sub_f32_e32 v126, v118, v110
	v_sub_f32_e32 v127, v119, v111
	v_fma_f32 v125, -v130, v124, v125
	v_fma_f32 v126, -v131, v124, v126
	v_fma_f32 v127, -v133, v124, v127
	s_waitcnt lgkmcnt(13)
	v_mul_f32_e32 v112, v176, v100
	s_waitcnt lgkmcnt(11)
	v_mul_f32_e32 v113, v184, v100
	v_fma_f32 v126, -v132, v125, v126
	v_fma_f32 v127, -v134, v125, v127
	s_waitcnt lgkmcnt(9)
	v_mul_f32_e32 v114, v192, v100
	s_waitcnt lgkmcnt(7)
	v_mul_f32_e32 v115, v200, v100
	v_fma_f32 v127, -v135, v126, v127
	v_fmac_f32_e32 v112, v177, v101
	v_fmac_f32_e32 v113, v185, v101
	v_cndmask_b32_e64 v106, v106, v124, s[6:7]
	v_fmac_f32_e32 v114, v193, v101
	v_cndmask_b32_e64 v106, v106, v125, s[8:9]
	v_fmac_f32_e32 v115, v201, v101
	v_cndmask_b32_e64 v106, v106, v126, s[10:11]
	v_fmac_f32_e32 v112, v178, v102
	v_cndmask_b32_e64 v106, v106, v127, s[12:13]
	v_fmac_f32_e32 v113, v186, v102
	v_fmac_f32_e32 v114, v194, v102
	v_fmac_f32_e32 v115, v202, v102
	v_fmac_f32_e32 v112, v179, v103
	v_fmac_f32_e32 v113, v187, v103
	v_fmac_f32_e32 v114, v195, v103
	v_fmac_f32_e32 v115, v203, v103
	v_fmac_f32_e32 v112, v180, v104
	v_fmac_f32_e32 v113, v188, v104
	v_fmac_f32_e32 v114, v196, v104
	s_waitcnt lgkmcnt(6)
	v_fmac_f32_e32 v115, v238, v104
	v_fmac_f32_e32 v112, v181, v105
	v_fmac_f32_e32 v113, v189, v105
	v_fmac_f32_e32 v114, v197, v105
	v_fmac_f32_e32 v115, v239, v105
	v_fmac_f32_e32 v112, v182, v106
	v_fmac_f32_e32 v113, v190, v106
	v_fmac_f32_e32 v114, v198, v106
	v_fmac_f32_e32 v115, v240, v106
	s_waitcnt lgkmcnt(0)
	ds_read_b128 v[206:209], v128 offset:14336
	ds_read_b128 v[210:213], v128 offset:14352
	ds_read_b128 v[214:217], v128 offset:14592
	ds_read_b128 v[218:221], v128 offset:14608
	ds_read_b128 v[222:225], v128 offset:14848
	ds_read_b128 v[226:229], v128 offset:14864
	ds_read_b128 v[230:233], v128 offset:15104
	ds_read_b128 v[234:237], v128 offset:15120
	ds_read_b32 v130, v129 offset:14620
	ds_read_b32 v131, v129 offset:14876
	ds_read_b32 v132, v129 offset:14908
	ds_read_b32 v133, v129 offset:15132
	ds_read_b32 v134, v129 offset:15164
	ds_read_b32 v135, v129 offset:15196
	v_add_f32_dpp v112, v112, v112 quad_perm:[1,0,3,2] row_mask:0xf bank_mask:0xf bound_ctrl:1
	v_add_f32_dpp v113, v113, v113 quad_perm:[1,0,3,2] row_mask:0xf bank_mask:0xf bound_ctrl:1
	v_cmp_eq_u32_e32 vcc, 56, v0
	v_add_f32_dpp v114, v114, v114 quad_perm:[1,0,3,2] row_mask:0xf bank_mask:0xf bound_ctrl:1
	v_add_f32_dpp v115, v115, v115 quad_perm:[1,0,3,2] row_mask:0xf bank_mask:0xf bound_ctrl:1
	v_cndmask_b32_e64 v116, 0, 1.0, vcc
	v_cmp_eq_u32_e32 vcc, 57, v0
	v_add_f32_dpp v112, v112, v112 quad_perm:[2,3,0,1] row_mask:0xf bank_mask:0xf bound_ctrl:1
	v_add_f32_dpp v113, v113, v113 quad_perm:[2,3,0,1] row_mask:0xf bank_mask:0xf bound_ctrl:1
	v_cndmask_b32_e64 v117, 0, 1.0, vcc
	v_cmp_eq_u32_e32 vcc, 58, v0
	v_add_f32_dpp v114, v114, v114 quad_perm:[2,3,0,1] row_mask:0xf bank_mask:0xf bound_ctrl:1
	v_add_f32_dpp v115, v115, v115 quad_perm:[2,3,0,1] row_mask:0xf bank_mask:0xf bound_ctrl:1
	v_cndmask_b32_e64 v118, 0, 1.0, vcc
	v_cmp_eq_u32_e32 vcc, 59, v0
	v_add_f32_dpp v112, v112, v112 row_half_mirror row_mask:0xf bank_mask:0xf bound_ctrl:1
	v_add_f32_dpp v113, v113, v113 row_half_mirror row_mask:0xf bank_mask:0xf bound_ctrl:1
	v_cndmask_b32_e64 v119, 0, 1.0, vcc
	v_add_f32_dpp v114, v114, v114 row_half_mirror row_mask:0xf bank_mask:0xf bound_ctrl:1
	v_add_f32_dpp v115, v115, v115 row_half_mirror row_mask:0xf bank_mask:0xf bound_ctrl:1
	v_sub_f32_e32 v124, v120, v112
	v_sub_f32_e32 v125, v121, v113
	v_sub_f32_e32 v126, v122, v114
	v_sub_f32_e32 v127, v123, v115
	v_fma_f32 v125, -v146, v124, v125
	v_fma_f32 v126, -v147, v124, v126
	v_fma_f32 v127, -v149, v124, v127
	s_waitcnt lgkmcnt(13)
	v_mul_f32_e32 v108, v206, v100
	s_waitcnt lgkmcnt(11)
	v_mul_f32_e32 v109, v214, v100
	v_fma_f32 v126, -v148, v125, v126
	v_fma_f32 v127, -v150, v125, v127
	s_waitcnt lgkmcnt(9)
	v_mul_f32_e32 v110, v222, v100
	s_waitcnt lgkmcnt(7)
	v_mul_f32_e32 v111, v230, v100
	v_fma_f32 v127, -v151, v126, v127
	v_fmac_f32_e32 v108, v207, v101
	v_fmac_f32_e32 v109, v215, v101
	v_cndmask_b32_e64 v106, v106, v124, s[14:15]
	v_fmac_f32_e32 v110, v223, v101
	v_cndmask_b32_e64 v106, v106, v125, s[16:17]
	v_fmac_f32_e32 v111, v231, v101
	v_cndmask_b32_e64 v106, v106, v126, s[18:19]
	v_fmac_f32_e32 v108, v208, v102
	v_cndmask_b32_e64 v106, v106, v127, s[20:21]
	v_fmac_f32_e32 v109, v216, v102
	v_fmac_f32_e32 v110, v224, v102
	v_fmac_f32_e32 v111, v232, v102
	v_fmac_f32_e32 v108, v209, v103
	v_fmac_f32_e32 v109, v217, v103
	v_fmac_f32_e32 v110, v225, v103
	v_fmac_f32_e32 v111, v233, v103
	v_fmac_f32_e32 v108, v210, v104
	v_fmac_f32_e32 v109, v218, v104
	v_fmac_f32_e32 v110, v226, v104
	s_waitcnt lgkmcnt(6)
	v_fmac_f32_e32 v111, v234, v104
	v_fmac_f32_e32 v108, v211, v105
	v_fmac_f32_e32 v109, v219, v105
	v_fmac_f32_e32 v110, v227, v105
	v_fmac_f32_e32 v111, v235, v105
.Lsv_b14:
	v_fmac_f32_e32 v108, v212, v106
	v_fmac_f32_e32 v109, v220, v106
	v_fmac_f32_e32 v110, v228, v106
	v_fmac_f32_e32 v111, v236, v106
	s_waitcnt lgkmcnt(0)
	ds_read_b128 v[176:179], v128 offset:15360
	ds_read_b128 v[180:183], v128 offset:15376
	ds_read_b128 v[184:187], v128 offset:15616
	ds_read_b128 v[188:191], v128 offset:15632
	ds_read_b128 v[192:195], v128 offset:15872
	ds_read_b128 v[196:199], v128 offset:15888
	ds_read_b128 v[200:203], v128 offset:16128
	ds_read_b128 v[238:241], v128 offset:16144
	ds_read_b32 v146, v129 offset:15772
	ds_read_b32 v147, v129 offset:16028
	ds_read_b32 v148, v129 offset:16060
	ds_read_b32 v149, v129 offset:16284
	ds_read_b32 v150, v129 offset:16316
	ds_read_b32 v151, v129 offset:16348
	v_add_f32_dpp v108, v108, v108 quad_perm:[1,0,3,2] row_mask:0xf bank_mask:0xf bound_ctrl:1
	v_add_f32_dpp v109, v109, v109 quad_perm:[1,0,3,2] row_mask:0xf bank_mask:0xf bound_ctrl:1
	v_cmp_eq_u32_e32 vcc, 60, v0
	v_add_f32_dpp v110, v110, v110 quad_perm:[1,0,3,2] row_mask:0xf bank_mask:0xf bound_ctrl:1
	v_add_f32_dpp v111, v111, v111 quad_perm:[1,0,3,2] row_mask:0xf bank_mask:0xf bound_ctrl:1
	v_cndmask_b32_e64 v120, 0, 1.0, vcc
	v_cmp_eq_u32_e32 vcc, 61, v0
	v_add_f32_dpp v108, v108, v108 quad_perm:[2,3,0,1] row_mask:0xf bank_mask:0xf bound_ctrl:1
	v_add_f32_dpp v109, v109, v109 quad_perm:[2,3,0,1] row_mask:0xf bank_mask:0xf bound_ctrl:1
	v_cndmask_b32_e64 v121, 0, 1.0, vcc
	v_cmp_eq_u32_e32 vcc, 62, v0
	v_add_f32_dpp v110, v110, v110 quad_perm:[2,3,0,1] row_mask:0xf bank_mask:0xf bound_ctrl:1
	v_add_f32_dpp v111, v111, v111 quad_perm:[2,3,0,1] row_mask:0xf bank_mask:0xf bound_ctrl:1
	v_cndmask_b32_e64 v122, 0, 1.0, vcc
	v_cmp_eq_u32_e32 vcc, 63, v0
	v_add_f32_dpp v108, v108, v108 row_half_mirror row_mask:0xf bank_mask:0xf bound_ctrl:1
	v_add_f32_dpp v109, v109, v109 row_half_mirror row_mask:0xf bank_mask:0xf bound_ctrl:1
	v_cndmask_b32_e64 v123, 0, 1.0, vcc
	v_add_f32_dpp v110, v110, v110 row_half_mirror row_mask:0xf bank_mask:0xf bound_ctrl:1
	v_add_f32_dpp v111, v111, v111 row_half_mirror row_mask:0xf bank_mask:0xf bound_ctrl:1
	v_sub_f32_e32 v124, v116, v108
	v_sub_f32_e32 v125, v117, v109
	v_sub_f32_e32 v126, v118, v110
	v_sub_f32_e32 v127, v119, v111
	v_fma_f32 v125, -v130, v124, v125
	v_fma_f32 v126, -v131, v124, v126
	v_fma_f32 v127, -v133, v124, v127
	s_waitcnt lgkmcnt(13)
	v_mul_f32_e32 v112, v176, v100
	s_waitcnt lgkmcnt(11)
	v_mul_f32_e32 v113, v184, v100
	v_fma_f32 v126, -v132, v125, v126
	v_fma_f32 v127, -v134, v125, v127
	s_waitcnt lgkmcnt(9)
	v_mul_f32_e32 v114, v192, v100
	s_waitcnt lgkmcnt(7)
	v_mul_f32_e32 v115, v200, v100
	v_fma_f32 v127, -v135, v126, v127
	v_fmac_f32_e32 v112, v177, v101
	v_fmac_f32_e32 v113, v185, v101
	v_cndmask_b32_e64 v107, v107, v124, s[6:7]
	v_fmac_f32_e32 v114, v193, v101
	v_cndmask_b32_e64 v107, v107, v125, s[8:9]
	v_fmac_f32_e32 v115, v201, v101
	v_cndmask_b32_e64 v107, v107, v126, s[10:11]
	v_fmac_f32_e32 v112, v178, v102
	v_cndmask_b32_e64 v107, v107, v127, s[12:13]
	v_fmac_f32_e32 v113, v186, v102
	v_fmac_f32_e32 v114, v194, v102
	v_fmac_f32_e32 v115, v202, v102
	v_fmac_f32_e32 v112, v179, v103
	v_fmac_f32_e32 v113, v187, v103
	v_fmac_f32_e32 v114, v195, v103
	v_fmac_f32_e32 v115, v203, v103
	v_fmac_f32_e32 v112, v180, v104
	v_fmac_f32_e32 v113, v188, v104
	v_fmac_f32_e32 v114, v196, v104
	s_waitcnt lgkmcnt(6)
	v_fmac_f32_e32 v115, v238, v104
	v_fmac_f32_e32 v112, v181, v105
	v_fmac_f32_e32 v113, v189, v105
	v_fmac_f32_e32 v114, v197, v105
	v_fmac_f32_e32 v115, v239, v105
	v_fmac_f32_e32 v112, v182, v106
	v_fmac_f32_e32 v113, v190, v106
	v_fmac_f32_e32 v114, v198, v106
	v_fmac_f32_e32 v115, v240, v106
	v_fmac_f32_e32 v112, v183, v107
	v_fmac_f32_e32 v113, v191, v107
	v_fmac_f32_e32 v114, v199, v107
	v_fmac_f32_e32 v115, v241, v107
	v_add_f32_dpp v112, v112, v112 quad_perm:[1,0,3,2] row_mask:0xf bank_mask:0xf bound_ctrl:1
	v_add_f32_dpp v113, v113, v113 quad_perm:[1,0,3,2] row_mask:0xf bank_mask:0xf bound_ctrl:1
	v_add_f32_dpp v114, v114, v114 quad_perm:[1,0,3,2] row_mask:0xf bank_mask:0xf bound_ctrl:1
	v_add_f32_dpp v115, v115, v115 quad_perm:[1,0,3,2] row_mask:0xf bank_mask:0xf bound_ctrl:1
	v_add_f32_dpp v112, v112, v112 quad_perm:[2,3,0,1] row_mask:0xf bank_mask:0xf bound_ctrl:1
	v_add_f32_dpp v113, v113, v113 quad_perm:[2,3,0,1] row_mask:0xf bank_mask:0xf bound_ctrl:1
	v_add_f32_dpp v114, v114, v114 quad_perm:[2,3,0,1] row_mask:0xf bank_mask:0xf bound_ctrl:1
	v_add_f32_dpp v115, v115, v115 quad_perm:[2,3,0,1] row_mask:0xf bank_mask:0xf bound_ctrl:1
	v_add_f32_dpp v112, v112, v112 row_half_mirror row_mask:0xf bank_mask:0xf bound_ctrl:1
	v_add_f32_dpp v113, v113, v113 row_half_mirror row_mask:0xf bank_mask:0xf bound_ctrl:1
	v_add_f32_dpp v114, v114, v114 row_half_mirror row_mask:0xf bank_mask:0xf bound_ctrl:1
	v_add_f32_dpp v115, v115, v115 row_half_mirror row_mask:0xf bank_mask:0xf bound_ctrl:1
	v_sub_f32_e32 v124, v120, v112
	v_sub_f32_e32 v125, v121, v113
	v_sub_f32_e32 v126, v122, v114
	v_sub_f32_e32 v127, v123, v115
	s_waitcnt lgkmcnt(5)
	v_fma_f32 v125, -v146, v124, v125
	s_waitcnt lgkmcnt(4)
	v_fma_f32 v126, -v147, v124, v126
	s_waitcnt lgkmcnt(2)
	v_fma_f32 v127, -v149, v124, v127
	v_fma_f32 v126, -v148, v125, v126
	s_waitcnt lgkmcnt(1)
	v_fma_f32 v127, -v150, v125, v127
	s_waitcnt lgkmcnt(0)
	v_fma_f32 v127, -v151, v126, v127
	v_cndmask_b32_e64 v107, v107, v124, s[14:15]
	v_cndmask_b32_e64 v107, v107, v125, s[16:17]
	v_cndmask_b32_e64 v107, v107, v126, s[18:19]
	v_cndmask_b32_e64 v107, v107, v127, s[20:21]
	v_lshl_add_u32 v152, v0, 2, 0
	v_add_u32_e32 v153, 0x15c00, v152
	v_add_u32_e32 v154, 0x15e00, v152
	v_add_u32_e32 v155, 0x15f00, v152
	ds_read_b32 v153, v153
	ds_read_b32 v154, v154
	ds_read_b32 v155, v155
	v_mul_u32_u24_e32 v156, 0x48, v2
	v_add_lshl_u32 v156, v0, v156, 1
	v_readlane_b32 s6, v244, 27
	v_readlane_b32 s7, v244, 32
	s_lshl_b64 s[8:9], s[36:37], 14
	s_mov_b32 s36, s2
	s_nop 1
	v_add_u32_e32 v157, s6, v156
	v_add_u32_e32 v156, s7, v156
	s_waitcnt lgkmcnt(0)
	v_mul_f32_e32 v154, v153, v154
	v_mul_f32_e32 v154, v154, v155
	v_mul_f32_e32 v158, v100, v153
	v_mul_f32_e32 v159, v100, v154
	v_cvt_pk_bf16_f32 v158, v158, v158
	v_cvt_pk_bf16_f32 v159, v159, v159
	ds_write_b16 v157, v158 offset:0
	ds_write_b16 v156, v159 offset:0
	v_mul_f32_e32 v158, v101, v153
	v_mul_f32_e32 v159, v101, v154
	v_cvt_pk_bf16_f32 v158, v158, v158
	v_cvt_pk_bf16_f32 v159, v159, v159
	ds_write_b16 v157, v158 offset:1152
	ds_write_b16 v156, v159 offset:1152
	v_mul_f32_e32 v158, v102, v153
	v_mul_f32_e32 v159, v102, v154
	v_cvt_pk_bf16_f32 v158, v158, v158
	v_cvt_pk_bf16_f32 v159, v159, v159
	ds_write_b16 v157, v158 offset:2304
	ds_write_b16 v156, v159 offset:2304
	v_mul_f32_e32 v158, v103, v153
	v_mul_f32_e32 v159, v103, v154
	v_cvt_pk_bf16_f32 v158, v158, v158
	v_cvt_pk_bf16_f32 v159, v159, v159
	ds_write_b16 v157, v158 offset:3456
	ds_write_b16 v156, v159 offset:3456
	v_mul_f32_e32 v158, v104, v153
	v_mul_f32_e32 v159, v104, v154
	v_cvt_pk_bf16_f32 v158, v158, v158
	v_cvt_pk_bf16_f32 v159, v159, v159
	ds_write_b16 v157, v158 offset:4608
	ds_write_b16 v156, v159 offset:4608
	v_mul_f32_e32 v158, v105, v153
	v_mul_f32_e32 v159, v105, v154
	v_cvt_pk_bf16_f32 v158, v158, v158
	v_cvt_pk_bf16_f32 v159, v159, v159
	ds_write_b16 v157, v158 offset:5760
	ds_write_b16 v156, v159 offset:5760
	v_mul_f32_e32 v158, v106, v153
	v_mul_f32_e32 v159, v106, v154
	v_cvt_pk_bf16_f32 v158, v158, v158
	v_cvt_pk_bf16_f32 v159, v159, v159
	ds_write_b16 v157, v158 offset:6912
	ds_write_b16 v156, v159 offset:6912
	v_mul_f32_e32 v158, v107, v153
	v_mul_f32_e32 v159, v107, v154
	v_cvt_pk_bf16_f32 v158, v158, v158
	v_cvt_pk_bf16_f32 v159, v159, v159
	ds_write_b16 v157, v158 offset:8064
	ds_write_b16 v156, v159 offset:8064
	v_mul_u32_u24_e32 v0, 0x48, v46
	v_lshlrev_b32_e32 v0, 1, v0
	v_add3_u32 v84, s6, v0, v48
	s_waitcnt lgkmcnt(0)
	s_barrier
	ds_read_b128 v[2:5], v84
	v_lshl_or_b32 v46, v43, 4, v46
	s_movk_i32 s6, 0x90
	v_mul_lo_u32 v6, v46, s6
	v_add3_u32 v56, 0, v6, v48
	ds_read_b128 v[6:9], v56 offset:35840
	ds_read_b128 v[10:13], v84 offset:64
	ds_read_b128 v[14:17], v56 offset:35904
	s_waitcnt lgkmcnt(2)
	v_mfma_f32_16x16x32_bf16 v[2:5], v[2:5], v[6:9], 0
	v_add3_u32 v0, s7, v0, v48
	ds_read_b128 v[42:45], v0
	ds_read_b128 v[48:51], v56 offset:17408
	ds_read_b128 v[52:55], v0 offset:64
	s_add_u32 s6, s22, s8
	s_waitcnt lgkmcnt(3)
	v_mfma_f32_16x16x32_bf16 v[2:5], v[10:13], v[14:17], v[2:5]
	ds_read_b128 v[10:13], v56 offset:17472
	s_addc_u32 s7, s23, s9
	v_lshl_add_u32 v46, v47, 7, v46
	s_waitcnt lgkmcnt(2)
	v_mfma_f32_16x16x32_bf16 v[42:45], v[42:45], v[48:51], 0
	ds_read_b128 v[60:63], v0 offset:2304
	ds_read_b128 v[64:67], v0 offset:2368
	s_add_u32 s8, s59, s8
	s_waitcnt lgkmcnt(2)
	v_mfma_f32_16x16x32_bf16 v[42:45], v[52:55], v[10:13], v[42:45]
	v_ashrrev_i32_e32 v47, 31, v46
	s_addc_u32 s9, s64, s9
	v_lshlrev_b64 v[56:57], 1, v[46:47]
	v_cvt_pk_bf16_f32 v2, v2, s0
	v_lshl_add_u64 v[80:81], s[8:9], 0, v[56:57]
	ds_read_b128 v[52:55], v84 offset:2304
	global_store_short v[80:81], v2, off
	s_nop 0
	v_cvt_pk_bf16_f32 v2, v42, s0
	v_lshl_add_u64 v[82:83], s[6:7], 0, v[56:57]
	global_store_short v[82:83], v2, off
	v_cvt_pk_bf16_f32 v2, v3, s0
	global_store_short v[80:81], v2, off offset:256
	v_cvt_pk_bf16_f32 v2, v43, s0
	ds_read_b128 v[56:59], v84 offset:2368
	global_store_short v[82:83], v2, off offset:256
	v_cvt_pk_bf16_f32 v2, v4, s0
	global_store_short v[80:81], v2, off offset:512
	v_cvt_pk_bf16_f32 v2, v44, s0
	global_store_short v[82:83], v2, off offset:512
	v_cvt_pk_bf16_f32 v42, v5, s0
	s_waitcnt lgkmcnt(3)
	v_mfma_f32_16x16x32_bf16 v[2:5], v[60:63], v[48:51], 0
	global_store_short v[80:81], v42, off offset:768
	v_cvt_pk_bf16_f32 v42, v45, s0
	global_store_short v[82:83], v42, off offset:768
	s_waitcnt lgkmcnt(1)
	v_mfma_f32_16x16x32_bf16 v[52:55], v[52:55], v[6:9], 0
	v_add_u32_e32 v42, 0x800, v46
	v_ashrrev_i32_e32 v43, 31, v42
	v_lshlrev_b64 v[42:43], 1, v[42:43]
	v_mfma_f32_16x16x32_bf16 v[2:5], v[64:67], v[10:13], v[2:5]
	v_lshl_add_u64 v[44:45], s[8:9], 0, v[42:43]
	v_lshl_add_u64 v[42:43], s[6:7], 0, v[42:43]
	ds_read_b128 v[60:63], v0 offset:4672
	s_waitcnt lgkmcnt(1)
	v_mfma_f32_16x16x32_bf16 v[52:55], v[56:59], v[14:17], v[52:55]
	ds_read_b128 v[56:59], v84 offset:4672
	s_nop 1
	v_cvt_pk_bf16_f32 v2, v2, s0
	global_store_short v[42:43], v2, off
	v_add_u32_e32 v42, 0x880, v46
	v_ashrrev_i32_e32 v43, 31, v42
	s_nop 0
	v_cvt_pk_bf16_f32 v47, v52, s0
	v_lshlrev_b64 v[42:43], 1, v[42:43]
	global_store_short v[44:45], v47, off
	v_cvt_pk_bf16_f32 v2, v53, s0
	v_lshl_add_u64 v[44:45], s[8:9], 0, v[42:43]
	global_store_short v[44:45], v2, off
	v_cvt_pk_bf16_f32 v44, v3, s0
	v_lshl_add_u64 v[2:3], s[6:7], 0, v[42:43]
	global_store_short v[2:3], v44, off
	v_add_u32_e32 v2, 0x900, v46
	v_ashrrev_i32_e32 v3, 31, v2
	v_lshlrev_b64 v[2:3], 1, v[2:3]
	ds_read_b128 v[42:45], v84 offset:4608
	v_cvt_pk_bf16_f32 v47, v54, s0
	v_lshl_add_u64 v[52:53], s[8:9], 0, v[2:3]
	v_cvt_pk_bf16_f32 v4, v4, s0
	v_lshl_add_u64 v[2:3], s[6:7], 0, v[2:3]
	global_store_short v[52:53], v47, off
	global_store_short v[2:3], v4, off
	v_cvt_pk_bf16_f32 v4, v55, s0
	ds_read_b128 v[52:55], v0 offset:4608
	s_waitcnt lgkmcnt(1)
	v_mfma_f32_16x16x32_bf16 v[42:45], v[42:45], v[6:9], 0
	v_add_u32_e32 v2, 0x980, v46
	v_ashrrev_i32_e32 v3, 31, v2
	v_lshlrev_b64 v[2:3], 1, v[2:3]
	s_waitcnt lgkmcnt(0)
	v_mfma_f32_16x16x32_bf16 v[52:55], v[52:55], v[48:51], 0
	s_and_b64 vcc, exec, s[38:39]
	v_mfma_f32_16x16x32_bf16 v[42:45], v[56:59], v[14:17], v[42:45]
	v_lshl_add_u64 v[56:57], s[8:9], 0, v[2:3]
	global_store_short v[56:57], v4, off
	v_cvt_pk_bf16_f32 v4, v5, s0
	v_lshl_add_u64 v[2:3], s[6:7], 0, v[2:3]
	global_store_short v[2:3], v4, off
	v_mfma_f32_16x16x32_bf16 v[2:5], v[60:63], v[10:13], v[52:55]
	s_nop 1
	v_cvt_pk_bf16_f32 v42, v42, s0
	v_cvt_pk_bf16_f32 v44, v44, s0
	ds_read_b128 v[56:59], v84 offset:6976
	v_add_u32_e32 v52, 0x1000, v46
	v_ashrrev_i32_e32 v53, 31, v52
	v_lshlrev_b64 v[52:53], 1, v[52:53]
	v_lshl_add_u64 v[54:55], s[8:9], 0, v[52:53]
	global_store_short v[54:55], v42, off
	v_cvt_pk_bf16_f32 v2, v2, s0
	v_lshl_add_u64 v[52:53], s[6:7], 0, v[52:53]
	v_add_u32_e32 v42, 0x1080, v46
	global_store_short v[52:53], v2, off
	v_cvt_pk_bf16_f32 v2, v43, s0
	v_ashrrev_i32_e32 v43, 31, v42
	v_lshlrev_b64 v[42:43], 1, v[42:43]
	v_lshl_add_u64 v[52:53], s[8:9], 0, v[42:43]
	global_store_short v[52:53], v2, off
	v_cvt_pk_bf16_f32 v47, v3, s0
	v_lshl_add_u64 v[2:3], s[6:7], 0, v[42:43]
	ds_read_b128 v[52:55], v84 offset:6912
	global_store_short v[2:3], v47, off
	v_add_u32_e32 v2, 0x1100, v46
	v_ashrrev_i32_e32 v3, 31, v2
	v_lshlrev_b64 v[2:3], 1, v[2:3]
	v_lshl_add_u64 v[42:43], s[8:9], 0, v[2:3]
	v_cvt_pk_bf16_f32 v4, v4, s0
	v_lshl_add_u64 v[2:3], s[6:7], 0, v[2:3]
	global_store_short v[42:43], v44, off
	global_store_short v[2:3], v4, off
	v_cvt_pk_bf16_f32 v4, v45, s0
	ds_read_b128 v[42:45], v0 offset:6912
	s_waitcnt lgkmcnt(1)
	v_mfma_f32_16x16x32_bf16 v[6:9], v[52:55], v[6:9], 0
	ds_read_b128 v[52:55], v0 offset:6976
	v_add_u32_e32 v2, 0x1180, v46
	v_ashrrev_i32_e32 v3, 31, v2
	v_lshlrev_b64 v[2:3], 1, v[2:3]
	v_mfma_f32_16x16x32_bf16 v[6:9], v[56:59], v[14:17], v[6:9]
	v_lshl_add_u64 v[14:15], s[8:9], 0, v[2:3]
	global_store_short v[14:15], v4, off
	v_cvt_pk_bf16_f32 v0, v5, s0
	s_waitcnt lgkmcnt(1)
	v_mfma_f32_16x16x32_bf16 v[14:17], v[42:45], v[48:51], 0
	v_lshl_add_u64 v[2:3], s[6:7], 0, v[2:3]
	global_store_short v[2:3], v0, off
	s_nop 0
	v_cvt_pk_bf16_f32 v0, v6, s0
	s_waitcnt lgkmcnt(0)
	v_mfma_f32_16x16x32_bf16 v[2:5], v[52:55], v[10:13], v[14:17]
	v_add_u32_e32 v10, 0x1800, v46
	v_ashrrev_i32_e32 v11, 31, v10
	v_lshlrev_b64 v[10:11], 1, v[10:11]
	v_lshl_add_u64 v[12:13], s[8:9], 0, v[10:11]
	global_store_short v[12:13], v0, off
	s_nop 2
	v_cvt_pk_bf16_f32 v0, v2, s0
	v_lshl_add_u64 v[10:11], s[6:7], 0, v[10:11]
	v_add_u32_e32 v6, 0x1880, v46
	global_store_short v[10:11], v0, off
	v_cvt_pk_bf16_f32 v0, v7, s0
	v_ashrrev_i32_e32 v7, 31, v6
	v_lshlrev_b64 v[6:7], 1, v[6:7]
	v_lshl_add_u64 v[10:11], s[8:9], 0, v[6:7]
	global_store_short v[10:11], v0, off
	v_cvt_pk_bf16_f32 v0, v3, s0
	v_lshl_add_u64 v[2:3], s[6:7], 0, v[6:7]
	global_store_short v[2:3], v0, off
	v_add_u32_e32 v2, 0x1900, v46
	v_ashrrev_i32_e32 v3, 31, v2
	v_lshlrev_b64 v[2:3], 1, v[2:3]
	v_cvt_pk_bf16_f32 v0, v8, s0
	v_lshl_add_u64 v[6:7], s[8:9], 0, v[2:3]
	global_store_short v[6:7], v0, off
	v_cvt_pk_bf16_f32 v0, v4, s0
	v_lshl_add_u64 v[2:3], s[6:7], 0, v[2:3]
	global_store_short v[2:3], v0, off
	v_add_u32_e32 v2, 0x1980, v46
	v_ashrrev_i32_e32 v3, 31, v2
	v_lshlrev_b64 v[2:3], 1, v[2:3]
	v_cvt_pk_bf16_f32 v0, v9, s0
	v_lshl_add_u64 v[6:7], s[8:9], 0, v[2:3]
	global_store_short v[6:7], v0, off
	v_cvt_pk_bf16_f32 v0, v5, s0
	v_lshl_add_u64 v[2:3], s[6:7], 0, v[2:3]
	global_store_short v[2:3], v0, off
	s_cbranch_vccnz .LBB0_601
